# v69 + P5 gamma/beta loads issued right after the residual add + P4 unit-top wait relaxed (no store drain) + page-stream preheaders: q unpack moved behind the first load burst (P1, P2 both groups)
# baseline (speedup 1.0000x reference)
.LBB0_234:
	v_mov_b32_e32 v131, v0
	v_readlane_b32 s16, v245, 9
	v_readfirstlane_b32 s0, v131
	s_ashr_i32 s69, s0, 6
	s_add_u32 s0, s96, 0xce00000
	v_readlane_b32 s17, v245, 10
	s_addc_u32 s1, s97, 0
	s_ashr_i32 s7, s6, 31
	v_readlane_b32 s18, v245, 11
	v_readlane_b32 s19, v245, 12
	s_mov_b64 s[8:9], s[16:17]
	s_lshl_b64 s[2:3], s[6:7], 2
	s_mov_b64 s[10:11], s[18:19]
	s_add_u32 s2, s10, s2
	s_addc_u32 s3, s11, s3
	v_mov_b32_e32 v187, 0
	global_load_dwordx2 v[18:19], v187, s[2:3]
	v_readlane_b32 s20, v245, 13
	v_readlane_b32 s24, v245, 17
	v_readlane_b32 s30, v245, 23
	s_lshl_b32 s12, s69, 4
	v_readlane_b32 s21, v245, 14
	v_readlane_b32 s25, v245, 18
	v_readlane_b32 s31, v245, 24
	s_ashr_i32 s2, s6, 4
	s_or_b32 s10, s12, 1
	s_or_b32 s20, s12, 2
	s_or_b32 s24, s12, 3
	s_or_b32 s30, s12, 4
	s_or_b32 s36, s12, 5
	s_or_b32 s58, s12, 6
	s_or_b32 s4, s12, 7
	s_ashr_i32 s13, s12, 31
	s_ashr_i32 s3, s2, 31
	s_ashr_i32 s11, s10, 31
	s_ashr_i32 s21, s20, 31
	s_ashr_i32 s25, s24, 31
	s_ashr_i32 s31, s30, 31
	s_ashr_i32 s37, s36, 31
	s_ashr_i32 s59, s58, 31
	s_ashr_i32 s5, s4, 31
	s_lshl_b64 s[38:39], s[12:13], 9
	s_lshl_b64 s[2:3], s[2:3], 10
	s_lshl_b64 s[40:41], s[10:11], 9
	s_lshl_b64 s[42:43], s[20:21], 9
	s_lshl_b64 s[44:45], s[24:25], 9
	s_lshl_b64 s[46:47], s[30:31], 9
	s_lshl_b64 s[48:49], s[36:37], 9
	s_lshl_b64 s[50:51], s[58:59], 9
	s_lshl_b64 s[56:57], s[4:5], 9
	v_and_b32_e32 v130, 63, v131
	s_add_u32 s2, s0, s2
	v_lshlrev_b32_e32 v186, 3, v130
	s_addc_u32 s3, s1, s3
	v_lshl_add_u64 v[10:11], s[2:3], 0, v[186:187]
	v_readlane_b32 s26, v245, 19
	v_readlane_b32 s27, v245, 20
	v_lshlrev_b32_e32 v138, 4, v130
	v_readlane_b32 s22, v245, 15
	v_readlane_b32 s23, v245, 16
	v_readlane_b32 s28, v245, 21
	v_readlane_b32 s29, v245, 22
	s_mov_b32 s87, 0x1000000
	v_add_co_u32_e32 v12, vcc, s87, v10
	v_bfe_u32 v132, v131, 2, 4
	s_nop 0
	v_addc_co_u32_e32 v13, vcc, 0, v11, vcc
	v_ashrrev_i32_e32 v136, 6, v131
	v_bfe_u32 v139, v131, 5, 1
	v_ashrrev_i32_e32 v137, 7, v131
	v_and_b32_e32 v134, 31, v131
	v_lshl_add_u32 v216, v131, 2, 0
	v_lshl_add_u64 v[188:189], s[0:1], 0, v[186:187]
	v_lshlrev_b32_e32 v186, 4, v134
	v_cmp_eq_u32_e32 vcc, 0, v134
	v_lshl_add_u32 v140, v136, 10, 0
	v_mov_b32_e32 v133, v187
	s_mov_b32 s89, 0xff800000
	v_add_u32_e32 v217, v140, v138
	s_waitcnt vmcnt(0)
	v_readfirstlane_b32 s2, v18
	s_ashr_i32 s3, s2, 31
	s_lshl_b64 s[2:3], s[2:3], 18
	s_add_u32 s26, s80, s2
	s_addc_u32 s27, s81, s3
	s_lshl_b64 s[4:5], s[4:5], 11
	s_add_u32 s8, s26, s4
	s_addc_u32 s9, s27, s5
	global_load_dwordx4 v[6:9], v138, s[8:9] offset:1024 nt
	global_load_dwordx4 v[2:5], v138, s[8:9] nt
	s_add_u32 s8, s78, s2
	s_addc_u32 s9, s79, s3
	s_add_u32 s16, s8, s4
	s_addc_u32 s17, s9, s5
	s_lshl_b64 s[4:5], s[12:13], 11
	s_add_u32 s2, s8, s4
	s_addc_u32 s3, s9, s5
	s_lshl_b64 s[18:19], s[10:11], 11
	global_load_dwordx4 v[42:45], v138, s[16:17] offset:1024 nt
	global_load_dwordx4 v[46:49], v138, s[16:17] nt
	s_add_u32 s16, s8, s18
	s_addc_u32 s17, s9, s19
	s_lshl_b64 s[22:23], s[20:21], 11
	s_add_u32 s20, s8, s22
	s_addc_u32 s21, s9, s23
	s_lshl_b64 s[28:29], s[24:25], 11
	s_add_u32 s24, s8, s28
	s_addc_u32 s25, s9, s29
	s_lshl_b64 s[30:31], s[30:31], 11
	s_add_u32 s10, s8, s30
	s_addc_u32 s11, s9, s31
	s_lshl_b64 s[36:37], s[36:37], 11
	global_load_dwordx4 v[86:89], v138, s[10:11] nt
	global_load_dwordx4 v[82:85], v138, s[10:11] offset:1024 nt
	s_add_u32 s10, s8, s36
	s_addc_u32 s11, s9, s37
	s_lshl_b64 s[58:59], s[58:59], 11
	global_load_dwordx4 v[78:81], v138, s[10:11] nt
	global_load_dwordx4 v[74:77], v138, s[10:11] offset:1024 nt
	s_add_u32 s10, s8, s58
	s_addc_u32 s11, s9, s59
	global_load_dwordx4 v[70:73], v138, s[10:11] nt
	global_load_dwordx4 v[66:69], v138, s[10:11] offset:1024 nt
	s_mov_b64 s[10:11], 0x1000000
	s_add_u32 s58, s26, s58
	v_lshl_add_u64 v[10:11], v[10:11], 0, s[10:11]
	s_addc_u32 s59, s27, s59
	global_load_dwordx2 v[198:199], v[10:11], off offset:512
	global_load_dwordx2 v[200:201], v[12:13], off
	global_load_dwordx4 v[14:17], v138, s[58:59] offset:1024 nt
	s_nop 0
	global_load_dwordx4 v[10:13], v138, s[58:59] nt
	s_add_u32 s36, s26, s36
	s_addc_u32 s37, s27, s37
	s_add_u32 s30, s26, s30
	s_addc_u32 s31, s27, s31
	s_add_u32 s28, s26, s28
	s_addc_u32 s29, s27, s29
	s_add_u32 s22, s26, s22
	s_addc_u32 s23, s27, s23
	s_add_u32 s18, s26, s18
	s_addc_u32 s19, s27, s19
	s_add_u32 s4, s26, s4
	s_addc_u32 s5, s27, s5
	v_readfirstlane_b32 s68, v19
	s_add_i32 s88, s33, -2
	global_load_dwordx4 v[22:25], v138, s[36:37] offset:1024 nt
	global_load_dwordx4 v[18:21], v138, s[36:37] nt
	global_load_dwordx4 v[90:93], v138, s[30:31] offset:1024 nt
	global_load_dwordx4 v[94:97], v138, s[30:31] nt
	global_load_dwordx4 v[50:53], v138, s[28:29] offset:1024 nt
	global_load_dwordx4 v[26:29], v138, s[28:29] nt
	global_load_dwordx4 v[102:105], v138, s[24:25] nt
	global_load_dwordx4 v[98:101], v138, s[24:25] offset:1024 nt
	global_load_dwordx4 v[54:57], v138, s[22:23] offset:1024 nt
	global_load_dwordx4 v[38:41], v138, s[22:23] nt
	global_load_dwordx4 v[110:113], v138, s[20:21] nt
	global_load_dwordx4 v[106:109], v138, s[20:21] offset:1024 nt
	global_load_dwordx4 v[58:61], v138, s[18:19] offset:1024 nt
	global_load_dwordx4 v[34:37], v138, s[18:19] nt
	global_load_dwordx4 v[118:121], v138, s[16:17] nt
	global_load_dwordx4 v[114:117], v138, s[16:17] offset:1024 nt
	global_load_dwordx4 v[62:65], v138, s[4:5] offset:1024 nt
	global_load_dwordx4 v[30:33], v138, s[4:5] nt
	global_load_dwordx4 v[126:129], v138, s[2:3] nt
	global_load_dwordx4 v[122:125], v138, s[2:3] offset:1024 nt
	s_waitcnt vmcnt(22)
	v_lshlrev_b32_e32 v219, 16, v198
	v_and_b32_e32 v220, 0xffff0000, v198
	v_lshlrev_b32_e32 v198, 16, v199
	v_and_b32_e32 v199, 0xffff0000, v199
	v_lshlrev_b32_e32 v221, 16, v200
	v_and_b32_e32 v222, 0xffff0000, v200
	v_lshlrev_b32_e32 v200, 16, v201
	v_and_b32_e32 v201, 0xffff0000, v201
	s_lshl_b32 s2, s69, 12
	s_add_i32 s2, s2, 0
	s_mulk_i32 s69, 0xf020
	v_add_u32_e32 v1, s2, v138
	s_add_i32 s2, s2, s69
	s_or_b32 s16, s12, 8
	v_add_u32_e32 v214, s2, v132
	v_lshlrev_b32_e32 v132, 1, v136
	v_and_or_b32 v132, v132, 2, v139
	s_ashr_i32 s17, s16, 31
	v_lshl_add_u32 v132, v132, 1, v137
	s_lshl_b64 s[18:19], s[16:17], 9
	s_or_b32 s16, s12, 9
	s_movk_i32 s4, 0x100
	v_lshl_add_u32 v215, v132, 2, 0
	v_and_b32_e32 v132, -8, v131
	s_movk_i32 s69, 0x88
	s_ashr_i32 s17, s16, 31
	v_cmp_gt_i32_e64 s[2:3], s4, v131
	v_cmp_eq_u32_e64 s[4:5], s4, v132
	v_mul_lo_u32 v132, v131, s69
	s_lshl_b64 s[22:23], s[16:17], 9
	s_or_b32 s16, s12, 10
	v_mov_b32_e32 v131, 0x1100
	s_ashr_i32 s17, s16, 31
	v_mad_i64_i32 v[134:135], s[0:1], s6, v131, v[186:187]
	v_lshlrev_b32_e32 v131, 2, v136
	s_lshl_b64 s[24:25], s[16:17], 9
	s_or_b32 s16, s12, 11
	v_and_b32_e32 v131, 4, v131
	v_lshlrev_b32_e32 v136, 1, v139
	s_ashr_i32 s17, s16, 31
	v_add3_u32 v131, v137, v131, v136
	s_lshl_b64 s[28:29], s[16:17], 9
	s_or_b32 s16, s12, 13
	v_mul_lo_u32 v136, v131, s69
	s_ashr_i32 s17, s16, 31
	v_ashrrev_i32_e32 v137, 31, v136
	s_or_b32 s20, s12, 12
	s_lshl_b64 s[36:37], s[16:17], 9
	s_or_b32 s16, s12, 14
	s_or_b32 s12, s12, 15
	v_lshl_add_u64 v[134:135], v[136:137], 2, v[134:135]
	s_ashr_i32 s21, s20, 31
	s_ashr_i32 s17, s16, 31
	s_ashr_i32 s13, s12, 31
	v_lshl_add_u64 v[134:135], s[96:97], 0, v[134:135]
	s_mov_b64 s[0:1], 0x23200020
	s_lshl_b64 s[30:31], s[20:21], 9
	s_lshl_b64 s[58:59], s[16:17], 9
	s_lshl_b64 s[84:85], s[12:13], 9
	v_lshl_add_u64 v[190:191], v[134:135], 0, s[0:1]
	s_mul_i32 s0, s6, 0x1100
	s_mul_hi_i32 s12, s6, 0x1100
	s_add_u32 s0, s96, s0
	v_add_u32_e32 v132, 0xffff7800, v132
	s_addc_u32 s1, s97, s12
	v_lshl_add_u64 v[132:133], v[132:133], 2, s[0:1]
	s_mov_b64 s[0:1], 0x23200000
	v_lshl_add_u64 v[192:193], v[132:133], 0, s[0:1]
	s_mov_b64 s[16:17], 0
	s_lshl_b64 s[12:13], s[18:19], 2
	v_lshlrev_b32_e32 v186, 4, v130
	s_lshl_b64 s[18:19], s[22:23], 2
	s_lshl_b64 s[20:21], s[24:25], 2
	s_lshl_b64 s[22:23], s[28:29], 2
	s_lshl_b64 s[24:25], s[30:31], 2
	s_lshl_b64 s[28:29], s[36:37], 2
	s_lshl_b64 s[30:31], s[58:59], 2
	s_lshl_b64 s[36:37], s[84:85], 2
	s_lshl_b64 s[38:39], s[38:39], 2
	s_lshl_b64 s[40:41], s[40:41], 2
	s_lshl_b64 s[42:43], s[42:43], 2
	s_lshl_b64 s[44:45], s[44:45], 2
	s_lshl_b64 s[46:47], s[46:47], 2
	s_lshl_b64 s[48:49], s[48:49], 2
	s_lshl_b64 s[50:51], s[50:51], 2
	s_lshl_b64 s[14:15], s[56:57], 2
	s_mov_b64 s[96:97], 0x1100
	s_branch .LBB0_236

.LBB0_624:
	v_readlane_b32 s4, v245, 2
	v_readlane_b32 s7, v245, 5
	s_bitcmp0_b32 s7, 5
	v_readlane_b32 s5, v245, 3
	v_readlane_b32 s6, v245, 4
	s_cbranch_scc1 .LBB0_635
	s_and_b32 s33, s95, -2
	s_ashr_i32 s1, s95, 31
	s_add_i32 s0, s33, s1
	s_xor_b32 s2, s0, s1
	v_cvt_f32_u32_e32 v1, s2
	v_readlane_b32 s0, v245, 54
	s_lshl_b32 s0, s0, 1
	s_sub_i32 s3, s33, s0
	v_rcp_iflag_f32_e32 v1, v1
	s_addk_i32 s3, 0x6ef
	s_ashr_i32 s4, s3, 31
	s_sub_i32 s5, 0, s2
	v_mul_f32_e32 v1, 0x4f7ffffe, v1
	v_cvt_u32_f32_e32 v1, v1
	s_xor_b32 s56, s4, s1
	s_abs_i32 s3, s3
	v_mov_b32_e32 v131, v0
	v_readfirstlane_b32 s1, v1
	s_mul_i32 s5, s5, s1
	s_mul_hi_u32 s4, s1, s5
	s_add_i32 s1, s1, s4
	s_mul_hi_u32 s1, s3, s1
	s_mul_i32 s4, s1, s2
	s_sub_i32 s3, s3, s4
	s_add_i32 s5, s1, 1
	s_sub_i32 s4, s3, s2
	s_cmp_ge_u32 s3, s2
	s_cselect_b32 s1, s5, s1
	s_cselect_b32 s3, s4, s3
	s_add_i32 s4, s1, 1
	s_cmp_ge_u32 s3, s2
	s_cselect_b32 s1, s4, s1
	s_xor_b32 s57, s1, s56
	s_sub_i32 s68, s57, s56
	s_cmp_lt_i32 s68, 1
	v_readfirstlane_b32 s1, v131
	s_cbranch_scc1 .LBB0_635
	s_add_u32 s2, s96, 0xce00000
	s_addc_u32 s3, s97, 0
	s_ashr_i32 s58, s1, 6
	s_ashr_i32 s1, s0, 31
	v_readlane_b32 s8, v245, 9
	s_add_i32 s6, s0, 0x110
	s_lshl_b64 s[0:1], s[0:1], 2
	v_readlane_b32 s10, v245, 11
	v_readlane_b32 s11, v245, 12
	s_add_u32 s0, s10, s0
	s_addc_u32 s1, s11, s1
	v_mov_b32_e32 v187, 0
	global_load_dword v1, v187, s[0:1] offset:1088
	s_cmp_lg_u32 s68, 1
	s_cselect_b32 s4, s33, 0
	s_ashr_i32 s5, s4, 31
	s_lshl_b64 s[4:5], s[4:5], 2
	s_add_u32 s0, s0, s4
	v_readlane_b32 s16, v245, 17
	v_readlane_b32 s20, v245, 21
	s_addc_u32 s1, s1, s5
	s_lshl_b32 s4, s58, 4
	v_readlane_b32 s9, v245, 10
	v_readlane_b32 s17, v245, 18
	v_readlane_b32 s21, v245, 22
	s_ashr_i32 s8, s6, 4
	global_load_dword v133, v187, s[0:1] offset:1088
	s_or_b32 s16, s4, 1
	s_or_b32 s20, s4, 2
	s_or_b32 s24, s4, 3
	s_or_b32 s30, s4, 4
	s_or_b32 s36, s4, 5
	s_or_b32 s60, s4, 6
	s_or_b32 s0, s4, 7
	s_ashr_i32 s5, s4, 31
	s_ashr_i32 s9, s8, 31
	s_ashr_i32 s17, s16, 31
	s_ashr_i32 s21, s20, 31
	s_ashr_i32 s25, s24, 31
	s_ashr_i32 s31, s30, 31
	s_ashr_i32 s37, s36, 31
	s_ashr_i32 s61, s60, 31
	s_ashr_i32 s1, s0, 31
	s_lshl_b64 s[6:7], s[4:5], 9
	s_lshl_b64 s[8:9], s[8:9], 10
	s_lshl_b64 s[38:39], s[16:17], 9
	s_lshl_b64 s[40:41], s[20:21], 9
	s_lshl_b64 s[42:43], s[24:25], 9
	s_lshl_b64 s[44:45], s[30:31], 9
	s_lshl_b64 s[46:47], s[36:37], 9
	s_lshl_b64 s[48:49], s[60:61], 9
	s_lshl_b64 s[50:51], s[0:1], 9
	v_and_b32_e32 v130, 63, v131
	s_add_u32 s8, s2, s8
	v_lshlrev_b32_e32 v186, 3, v130
	s_addc_u32 s9, s3, s9
	s_waitcnt vmcnt(0)
	v_lshl_add_u64 v[34:35], s[8:9], 0, v[186:187]
	v_readlane_b32 s12, v245, 13
	v_readlane_b32 s13, v245, 14
	v_lshlrev_b32_e32 v132, 4, v130
	v_readlane_b32 s14, v245, 15
	v_readlane_b32 s15, v245, 16
	v_readlane_b32 s18, v245, 19
	v_readlane_b32 s19, v245, 20
	v_readlane_b32 s22, v245, 23
	v_readlane_b32 s23, v245, 24
	s_mov_b32 s94, s85
	s_mov_b32 s69, 0x1000000
	v_add_co_u32_e32 v36, vcc, s69, v34
	v_bfe_u32 v134, v131, 2, 4
	s_nop 0
	v_addc_co_u32_e32 v37, vcc, 0, v35, vcc
	v_ashrrev_i32_e32 v137, 6, v131
	v_bfe_u32 v139, v131, 5, 1
	v_ashrrev_i32_e32 v138, 7, v131
	v_lshlrev_b32_e32 v135, 1, v139
	v_and_b32_e32 v136, 31, v131
	v_lshl_add_u64 v[188:189], s[2:3], 0, v[186:187]
	v_lshlrev_b32_e32 v186, 4, v136
	s_mov_b64 s[2:3], 0x23200020
	v_lshl_add_u32 v215, v131, 2, 0
	v_lshlrev_b32_e32 v216, 4, v130
	s_mov_b32 s90, 0xff800000
	v_readfirstlane_b32 s8, v1
	s_ashr_i32 s9, s8, 31
	s_lshl_b64 s[8:9], s[8:9], 18
	s_add_u32 s10, s80, s8
	s_addc_u32 s11, s81, s9
	s_lshl_b64 s[12:13], s[0:1], 11
	s_add_u32 s0, s10, s12
	s_addc_u32 s1, s11, s13
	global_load_dwordx4 v[6:9], v132, s[0:1] offset:1024 nt
	global_load_dwordx4 v[2:5], v132, s[0:1] nt
	s_add_u32 s0, s78, s8
	s_addc_u32 s1, s79, s9
	s_add_u32 s8, s0, s12
	s_addc_u32 s9, s1, s13
	s_lshl_b64 s[14:15], s[4:5], 11
	s_add_u32 s12, s0, s14
	s_addc_u32 s13, s1, s15
	s_lshl_b64 s[18:19], s[16:17], 11
	s_add_u32 s16, s0, s18
	s_addc_u32 s17, s1, s19
	s_lshl_b64 s[22:23], s[20:21], 11
	s_add_u32 s20, s0, s22
	s_addc_u32 s21, s1, s23
	s_lshl_b64 s[28:29], s[24:25], 11
	s_add_u32 s24, s0, s28
	global_load_dwordx4 v[26:29], v132, s[8:9] offset:1024 nt
	global_load_dwordx4 v[30:33], v132, s[8:9] nt
	s_addc_u32 s25, s1, s29
	s_lshl_b64 s[8:9], s[30:31], 11
	s_add_u32 s30, s0, s8
	s_addc_u32 s31, s1, s9
	s_lshl_b64 s[36:37], s[36:37], 11
	s_add_u32 s84, s0, s36
	s_addc_u32 s85, s1, s37
	s_lshl_b64 s[60:61], s[60:61], 11
	global_load_dwordx4 v[62:65], v132, s[84:85] nt
	global_load_dwordx4 v[58:61], v132, s[84:85] offset:1024 nt
	s_add_u32 s84, s0, s60
	s_addc_u32 s85, s1, s61
	s_add_u32 s60, s10, s60
	s_addc_u32 s61, s11, s61
	s_add_u32 s36, s10, s36
	s_addc_u32 s37, s11, s37
	global_load_dwordx4 v[54:57], v132, s[84:85] nt
	global_load_dwordx4 v[50:53], v132, s[84:85] offset:1024 nt
	global_load_dwordx4 v[22:25], v132, s[60:61] offset:1024 nt
	global_load_dwordx4 v[14:17], v132, s[60:61] nt
	global_load_dwordx4 v[18:21], v132, s[36:37] offset:1024 nt
	global_load_dwordx4 v[10:13], v132, s[36:37] nt
	s_add_u32 s36, s10, s8
	s_addc_u32 s37, s11, s9
	s_mov_b64 s[8:9], 0x1000000
	v_lshl_add_u64 v[34:35], v[34:35], 0, s[8:9]
	global_load_dwordx2 v[198:199], v[34:35], off offset:512
	s_nop 0
	global_load_dwordx2 v[200:201], v[36:37], off
	s_nop 0
	global_load_dwordx4 v[66:69], v132, s[36:37] offset:1024 nt
	global_load_dwordx4 v[70:73], v132, s[36:37] nt
	s_add_u32 s28, s10, s28
	s_addc_u32 s29, s11, s29
	s_add_u32 s22, s10, s22
	s_addc_u32 s23, s11, s23
	s_add_u32 s18, s10, s18
	s_addc_u32 s19, s11, s19
	s_add_u32 s14, s10, s14
	s_addc_u32 s15, s11, s15
	global_load_dwordx4 v[118:121], v132, s[30:31] nt
	global_load_dwordx4 v[114:117], v132, s[30:31] offset:1024 nt
	s_lshl_b32 s5, s58, 12
	s_add_i32 s5, s5, 0
	s_mulk_i32 s58, 0xf020
	v_add_u32_e32 v1, s5, v132
	s_add_i32 s5, s5, s58
	v_add_u32_e32 v214, s5, v134
	v_lshlrev_b32_e32 v134, 2, v137
	v_and_b32_e32 v134, 4, v134
	s_movk_i32 s37, 0x88
	v_add3_u32 v134, v138, v134, v135
	v_mul_lo_u32 v134, v134, s37
	v_ashrrev_i32_e32 v135, 31, v134
	v_lshl_add_u64 v[134:135], v[134:135], 2, v[186:187]
	v_lshl_add_u64 v[190:191], v[134:135], 0, s[2:3]
	v_readlane_b32 s2, v245, 51
	s_lshl_b32 s2, s2, 1
	v_readlane_b32 s3, v245, 52
	s_andn2_b32 s2, s2, 63
	s_lshl_b32 s3, s3, 1
	v_lshlrev_b32_e32 v134, 1, v137
	s_or_b32 s2, s2, s3
	v_and_or_b32 v134, v134, 2, v139
	s_add_i32 s86, s2, 0x110
	v_lshl_add_u32 v134, v134, 1, v138
	s_lshl_b32 s85, s33, 1
	s_movk_i32 s36, 0x100
	v_mul_lo_u32 v140, v131, s37
	s_ashr_i32 s87, s86, 31
	s_mul_i32 s3, s86, 0x1100
	v_lshl_add_u32 v186, v134, 2, 0
	v_and_b32_e32 v134, -8, v131
	s_mul_hi_i32 s2, s86, 0x1100
	v_lshl_add_u32 v137, v137, 10, 0
	v_mov_b32_e32 v135, v187
	s_mov_b32 s84, 2
	v_add_u32_e32 v217, v137, v132
	v_readfirstlane_b32 s26, v133
	global_load_dwordx4 v[74:77], v132, s[28:29] offset:1024 nt
	global_load_dwordx4 v[34:37], v132, s[28:29] nt
	global_load_dwordx4 v[94:97], v132, s[24:25] nt
	global_load_dwordx4 v[90:93], v132, s[24:25] offset:1024 nt
	global_load_dwordx4 v[78:81], v132, s[22:23] offset:1024 nt
	global_load_dwordx4 v[46:49], v132, s[22:23] nt
	global_load_dwordx4 v[102:105], v132, s[20:21] nt
	global_load_dwordx4 v[98:101], v132, s[20:21] offset:1024 nt
	global_load_dwordx4 v[82:85], v132, s[18:19] offset:1024 nt
	global_load_dwordx4 v[42:45], v132, s[18:19] nt
	global_load_dwordx4 v[110:113], v132, s[16:17] nt
	global_load_dwordx4 v[106:109], v132, s[16:17] offset:1024 nt
	global_load_dwordx4 v[86:89], v132, s[14:15] offset:1024 nt
	global_load_dwordx4 v[38:41], v132, s[14:15] nt
	global_load_dwordx4 v[126:129], v132, s[12:13] nt
	global_load_dwordx4 v[122:125], v132, s[12:13] offset:1024 nt
	s_waitcnt vmcnt(20)
	v_lshlrev_b32_e32 v219, 16, v198
	v_and_b32_e32 v220, 0xffff0000, v198
	v_lshlrev_b32_e32 v198, 16, v199
	v_and_b32_e32 v199, 0xffff0000, v199
	v_lshlrev_b32_e32 v221, 16, v200
	v_and_b32_e32 v222, 0xffff0000, v200
	v_lshlrev_b32_e32 v200, 16, v201
	v_and_b32_e32 v201, 0xffff0000, v201
	s_or_b32 s12, s4, 8
	s_ashr_i32 s13, s12, 31
	s_lshl_b64 s[14:15], s[12:13], 9
	s_or_b32 s12, s4, 9
	s_ashr_i32 s13, s12, 31
	s_lshl_b64 s[16:17], s[12:13], 9
	s_or_b32 s12, s4, 10
	s_ashr_i32 s13, s12, 31
	s_lshl_b64 s[18:19], s[12:13], 9
	s_or_b32 s12, s4, 11
	s_ashr_i32 s13, s12, 31
	s_lshl_b64 s[20:21], s[12:13], 9
	s_or_b32 s12, s4, 13
	s_ashr_i32 s13, s12, 31
	s_or_b32 s22, s4, 12
	s_lshl_b64 s[24:25], s[12:13], 9
	s_or_b32 s12, s4, 14
	s_or_b32 s4, s4, 15
	s_ashr_i32 s23, s22, 31
	s_ashr_i32 s13, s12, 31
	s_ashr_i32 s5, s4, 31
	s_lshl_b64 s[22:23], s[22:23], 9
	s_lshl_b64 s[28:29], s[12:13], 9
	s_lshl_b64 s[30:31], s[4:5], 9
	s_add_u32 s12, s96, s3
	v_cmp_eq_u32_e64 s[4:5], s36, v134
	v_add_u32_e32 v134, 0xffff7800, v140
	s_addc_u32 s13, s97, s2
	v_cmp_gt_i32_e64 s[2:3], s36, v131
	s_sub_i32 s88, s56, s57
	v_lshlrev_b64 v[192:193], 2, v[134:135]
	s_lshl_b64 s[14:15], s[14:15], 2
	s_lshl_b64 s[16:17], s[16:17], 2
	s_lshl_b64 s[18:19], s[18:19], 2
	s_lshl_b64 s[20:21], s[20:21], 2
	s_lshl_b64 s[22:23], s[22:23], 2
	s_lshl_b64 s[24:25], s[24:25], 2
	s_lshl_b64 s[28:29], s[28:29], 2
	s_lshl_b64 s[30:31], s[30:31], 2
	s_lshl_b64 s[36:37], s[6:7], 2
	s_lshl_b64 s[38:39], s[38:39], 2
	s_lshl_b64 s[40:41], s[40:41], 2
	s_lshl_b64 s[42:43], s[42:43], 2
	s_lshl_b64 s[44:45], s[44:45], 2
	s_lshl_b64 s[46:47], s[46:47], 2
	s_lshl_b64 s[48:49], s[48:49], 2
	s_lshl_b64 s[50:51], s[50:51], 2
	s_ashr_i32 s89, s33, 31
	v_cmp_eq_u32_e64 s[6:7], 0, v136
	s_branch .LBB0_628

.LBB0_882:
	v_readlane_b32 s0, v245, 2
	v_readlane_b32 s3, v245, 5
	s_bitcmp0_b32 s3, 5
	v_readlane_b32 s85, v245, 50
	v_readlane_b32 s92, v245, 43
	v_readlane_b32 s1, v245, 3
	v_readlane_b32 s2, v245, 4
	s_cbranch_scc1 .LBB0_893
	s_and_b32 s33, s95, -2
	s_ashr_i32 s1, s95, 31
	s_add_i32 s0, s33, s1
	s_xor_b32 s2, s0, s1
	v_cvt_f32_u32_e32 v1, s2
	v_readlane_b32 s0, v245, 54
	s_lshl_b32 s0, s0, 1
	s_sub_i32 s3, s33, s0
	v_rcp_iflag_f32_e32 v1, v1
	s_addk_i32 s3, 0x6ee
	s_ashr_i32 s4, s3, 31
	s_sub_i32 s5, 0, s2
	v_mul_f32_e32 v1, 0x4f7ffffe, v1
	v_cvt_u32_f32_e32 v1, v1
	s_xor_b32 s20, s4, s1
	s_abs_i32 s3, s3
	v_mov_b32_e32 v131, v0
	v_readfirstlane_b32 s1, v1
	s_mul_i32 s5, s5, s1
	s_mul_hi_u32 s4, s1, s5
	s_add_i32 s1, s1, s4
	s_mul_hi_u32 s1, s3, s1
	s_mul_i32 s4, s1, s2
	s_sub_i32 s3, s3, s4
	s_add_i32 s5, s1, 1
	s_sub_i32 s4, s3, s2
	s_cmp_ge_u32 s3, s2
	s_cselect_b32 s1, s5, s1
	s_cselect_b32 s3, s4, s3
	s_add_i32 s4, s1, 1
	s_cmp_ge_u32 s3, s2
	s_cselect_b32 s1, s4, s1
	s_xor_b32 s21, s1, s20
	s_sub_i32 s77, s21, s20
	s_cmp_lt_i32 s77, 1
	v_readfirstlane_b32 s1, v131
	s_cbranch_scc1 .LBB0_893
	s_add_u32 s10, s96, 0xce00000
	v_readlane_b32 s36, v245, 9
	s_addc_u32 s11, s97, 0
	s_ashr_i32 s16, s1, 6
	s_ashr_i32 s1, s0, 31
	v_readlane_b32 s38, v245, 11
	v_readlane_b32 s39, v245, 12
	s_add_i32 s4, s0, 0x111
	s_lshl_b64 s[0:1], s[0:1], 2
	s_mov_b64 s[14:15], s[38:39]
	s_add_u32 s0, s14, s0
	s_addc_u32 s1, s15, s1
	v_mov_b32_e32 v187, 0
	global_load_dword v1, v187, s[0:1] offset:1092
	s_cmp_lg_u32 s77, 1
	s_cselect_b32 s2, s33, 0
	s_ashr_i32 s3, s2, 31
	s_lshl_b64 s[2:3], s[2:3], 2
	s_add_u32 s0, s0, s2
	s_addc_u32 s1, s1, s3
	s_lshl_b32 s12, s16, 4
	s_ashr_i32 s2, s4, 4
	global_load_dword v22, v187, s[0:1] offset:1092
	s_or_b32 s18, s12, 1
	s_or_b32 s22, s12, 2
	s_or_b32 s24, s12, 3
	s_or_b32 s14, s12, 4
	s_or_b32 s6, s12, 5
	s_or_b32 s0, s12, 6
	s_or_b32 s4, s12, 7
	v_readlane_b32 s37, v245, 10
	v_readlane_b32 s40, v245, 13
	v_readlane_b32 s41, v245, 14
	v_readlane_b32 s42, v245, 15
	v_readlane_b32 s43, v245, 16
	v_readlane_b32 s44, v245, 17
	v_readlane_b32 s45, v245, 18
	v_readlane_b32 s46, v245, 19
	v_readlane_b32 s47, v245, 20
	v_readlane_b32 s48, v245, 21
	v_readlane_b32 s49, v245, 22
	s_ashr_i32 s13, s12, 31
	s_ashr_i32 s3, s2, 31
	s_ashr_i32 s19, s18, 31
	s_ashr_i32 s23, s22, 31
	s_ashr_i32 s25, s24, 31
	s_ashr_i32 s15, s14, 31
	s_ashr_i32 s7, s6, 31
	s_ashr_i32 s1, s0, 31
	s_ashr_i32 s5, s4, 31
	s_lshl_b64 s[30:31], s[12:13], 9
	s_lshl_b64 s[2:3], s[2:3], 10
	s_lshl_b64 s[36:37], s[18:19], 9
	s_lshl_b64 s[38:39], s[22:23], 9
	s_lshl_b64 s[40:41], s[24:25], 9
	s_lshl_b64 s[42:43], s[14:15], 9
	s_lshl_b64 s[44:45], s[6:7], 9
	s_lshl_b64 s[46:47], s[0:1], 9
	s_lshl_b64 s[48:49], s[4:5], 9
	v_and_b32_e32 v130, 63, v131
	s_add_u32 s2, s10, s2
	v_lshlrev_b32_e32 v186, 3, v130
	s_addc_u32 s3, s11, s3
	s_waitcnt vmcnt(0)
	v_lshl_add_u64 v[10:11], s[2:3], 0, v[186:187]
	v_readlane_b32 s50, v245, 23
	v_readlane_b32 s51, v245, 24
	v_lshlrev_b32_e32 v136, 4, v130
	s_mov_b32 s82, 0x1000000
	v_add_co_u32_e32 v12, vcc, s82, v10
	v_bfe_u32 v132, v131, 2, 4
	s_nop 0
	v_addc_co_u32_e32 v13, vcc, 0, v11, vcc
	v_ashrrev_i32_e32 v135, 6, v131
	v_bfe_u32 v138, v131, 5, 1
	v_ashrrev_i32_e32 v137, 7, v131
	v_and_b32_e32 v134, 31, v131
	v_lshl_add_u32 v216, v131, 2, 0
	v_lshl_add_u64 v[188:189], s[10:11], 0, v[186:187]
	v_lshlrev_b32_e32 v186, 4, v134
	v_lshl_add_u32 v139, v135, 10, 0
	s_mov_b64 s[10:11], 0x23201120
	v_mov_b32_e32 v133, v187
	s_mov_b32 s87, s85
	s_mov_b32 s68, 2
	s_mov_b32 s76, 0xff800000
	v_add_u32_e32 v217, v139, v136
	v_readfirstlane_b32 s2, v1
	s_ashr_i32 s3, s2, 31
	s_lshl_b64 s[2:3], s[2:3], 18
	s_add_u32 s50, s80, s2
	s_addc_u32 s51, s81, s3
	s_lshl_b64 s[4:5], s[4:5], 11
	s_add_u32 s8, s50, s4
	s_addc_u32 s9, s51, s5
	global_load_dwordx4 v[6:9], v136, s[8:9] offset:1024 nt
	global_load_dwordx4 v[2:5], v136, s[8:9] nt
	s_add_u32 s8, s78, s2
	s_addc_u32 s9, s79, s3
	s_add_u32 s28, s8, s4
	s_addc_u32 s29, s9, s5
	s_lshl_b64 s[4:5], s[12:13], 11
	s_add_u32 s2, s8, s4
	s_addc_u32 s3, s9, s5
	s_lshl_b64 s[18:19], s[18:19], 11
	global_load_dwordx4 v[66:69], v136, s[28:29] offset:1024 nt
	global_load_dwordx4 v[70:73], v136, s[28:29] nt
	s_add_u32 s28, s8, s18
	s_addc_u32 s29, s9, s19
	s_lshl_b64 s[22:23], s[22:23], 11
	s_add_u32 s56, s8, s22
	s_addc_u32 s57, s9, s23
	s_lshl_b64 s[24:25], s[24:25], 11
	s_add_u32 s58, s8, s24
	s_addc_u32 s59, s9, s25
	s_lshl_b64 s[14:15], s[14:15], 11
	s_add_u32 s72, s8, s14
	s_addc_u32 s73, s9, s15
	s_lshl_b64 s[6:7], s[6:7], 11
	s_add_u32 s74, s8, s6
	s_addc_u32 s75, s9, s7
	s_lshl_b64 s[0:1], s[0:1], 11
	s_add_u32 s52, s8, s0
	s_addc_u32 s53, s9, s1
	global_load_dwordx4 v[74:77], v136, s[52:53] nt
	global_load_dwordx4 v[78:81], v136, s[52:53] offset:1024 nt
	s_add_u32 s52, s50, s0
	s_addc_u32 s53, s51, s1
	s_mov_b64 s[0:1], 0x1000000
	v_lshl_add_u64 v[10:11], v[10:11], 0, s[0:1]
	global_load_dwordx2 v[198:199], v[10:11], off offset:512
	global_load_dwordx2 v[200:201], v[12:13], off
	s_add_u32 s6, s50, s6
	s_addc_u32 s7, s51, s7
	global_load_dwordx4 v[18:21], v136, s[52:53] offset:1024 nt
	global_load_dwordx4 v[10:13], v136, s[52:53] nt
	v_readfirstlane_b32 s26, v22
	s_movk_i32 s53, 0x88
	global_load_dwordx4 v[22:25], v136, s[6:7] offset:1024 nt
	global_load_dwordx4 v[14:17], v136, s[6:7] nt
	global_load_dwordx4 v[102:105], v136, s[74:75] nt
	global_load_dwordx4 v[98:101], v136, s[74:75] offset:1024 nt
	s_add_u32 s6, s50, s14
	s_addc_u32 s7, s51, s15
	global_load_dwordx4 v[58:61], v136, s[6:7] offset:1024 nt
	global_load_dwordx4 v[62:65], v136, s[6:7] nt
	global_load_dwordx4 v[118:121], v136, s[72:73] nt
	global_load_dwordx4 v[114:117], v136, s[72:73] offset:1024 nt
	s_add_u32 s6, s50, s24
	s_addc_u32 s7, s51, s25
	global_load_dwordx4 v[42:45], v136, s[6:7] offset:1024 nt
	global_load_dwordx4 v[26:29], v136, s[6:7] nt
	global_load_dwordx4 v[86:89], v136, s[58:59] nt
	global_load_dwordx4 v[82:85], v136, s[58:59] offset:1024 nt
	s_add_u32 s6, s50, s22
	s_addc_u32 s7, s51, s23
	global_load_dwordx4 v[46:49], v136, s[6:7] offset:1024 nt
	global_load_dwordx4 v[38:41], v136, s[6:7] nt
	global_load_dwordx4 v[94:97], v136, s[56:57] nt
	global_load_dwordx4 v[90:93], v136, s[56:57] offset:1024 nt
	s_add_u32 s6, s50, s18
	s_addc_u32 s7, s51, s19
	s_add_u32 s4, s50, s4
	s_addc_u32 s5, s51, s5
	global_load_dwordx4 v[50:53], v136, s[6:7] offset:1024 nt
	global_load_dwordx4 v[34:37], v136, s[6:7] nt
	global_load_dwordx4 v[110:113], v136, s[28:29] nt
	global_load_dwordx4 v[106:109], v136, s[28:29] offset:1024 nt
	global_load_dwordx4 v[54:57], v136, s[4:5] offset:1024 nt
	global_load_dwordx4 v[30:33], v136, s[4:5] nt
	global_load_dwordx4 v[126:129], v136, s[2:3] nt
	s_waitcnt vmcnt(25)
	v_lshlrev_b32_e32 v219, 16, v198
	v_and_b32_e32 v220, 0xffff0000, v198
	v_lshlrev_b32_e32 v198, 16, v199
	v_and_b32_e32 v199, 0xffff0000, v199
	v_lshlrev_b32_e32 v221, 16, v200
	v_and_b32_e32 v222, 0xffff0000, v200
	v_lshlrev_b32_e32 v200, 16, v201
	v_and_b32_e32 v201, 0xffff0000, v201
	global_load_dwordx4 v[122:125], v136, s[2:3] offset:1024 nt
	s_lshl_b32 s2, s16, 12
	s_add_i32 s4, s2, 0
	s_mulk_i32 s16, 0xf020
	v_add_u32_e32 v1, s4, v136
	s_add_i32 s4, s4, s16
	v_add_u32_e32 v214, s4, v132
	v_lshlrev_b32_e32 v132, 1, v135
	v_and_or_b32 v132, v132, 2, v138
	v_lshl_add_u32 v132, v132, 1, v137
	s_movk_i32 s6, 0x100
	v_lshl_add_u32 v215, v132, 2, 0
	v_and_b32_e32 v132, -8, v131
	v_cmp_gt_i32_e64 s[4:5], s6, v131
	v_cmp_eq_u32_e64 s[6:7], s6, v132
	v_mul_lo_u32 v132, v131, s53
	v_lshlrev_b32_e32 v131, 2, v135
	v_cmp_eq_u32_e64 s[2:3], 0, v134
	v_and_b32_e32 v131, 4, v131
	v_lshlrev_b32_e32 v134, 1, v138
	v_add3_u32 v131, v137, v131, v134
	v_mul_lo_u32 v134, v131, s53
	v_ashrrev_i32_e32 v135, 31, v134
	v_lshl_add_u64 v[134:135], v[134:135], 2, v[186:187]
	v_lshl_add_u64 v[190:191], v[134:135], 0, s[10:11]
	v_readlane_b32 s10, v245, 51
	s_lshl_b32 s10, s10, 1
	v_readlane_b32 s11, v245, 52
	s_or_b32 s14, s12, 8
	s_or_b32 s22, s12, 12
	s_or_b32 s16, s12, 9
	s_or_b32 s18, s12, 10
	s_or_b32 s24, s12, 11
	s_or_b32 s28, s12, 13
	s_or_b32 s56, s12, 14
	s_or_b32 s12, s12, 15
	s_andn2_b32 s10, s10, 63
	s_lshl_b32 s11, s11, 1
	s_ashr_i32 s13, s12, 31
	s_or_b32 s10, s10, s11
	s_ashr_i32 s15, s14, 31
	s_ashr_i32 s17, s16, 31
	s_ashr_i32 s19, s18, 31
	s_ashr_i32 s25, s24, 31
	s_ashr_i32 s23, s22, 31
	s_ashr_i32 s29, s28, 31
	s_ashr_i32 s57, s56, 31
	s_lshl_b64 s[58:59], s[12:13], 9
	s_add_i32 s12, s10, 0x110
	s_lshl_b32 s69, s33, 1
	s_lshl_b64 s[14:15], s[14:15], 9
	s_lshl_b64 s[16:17], s[16:17], 9
	s_lshl_b64 s[18:19], s[18:19], 9
	s_lshl_b64 s[24:25], s[24:25], 9
	s_lshl_b64 s[22:23], s[22:23], 9
	s_lshl_b64 s[28:29], s[28:29], 9
	s_lshl_b64 s[56:57], s[56:57], 9
	s_ashr_i32 s72, s12, 31
	s_mul_i32 s10, s12, 0x1100
	v_add_u32_e32 v132, 0xffff7800, v132
	s_mul_hi_i32 s11, s12, 0x1100
	s_add_u32 s10, s96, s10
	s_addc_u32 s11, s97, s11
	s_ashr_i32 s73, s33, 31
	v_lshlrev_b64 v[192:193], 2, v[132:133]
	s_or_b32 s74, s12, 1
	s_sub_i32 s75, s20, s21
	s_lshl_b64 s[12:13], s[14:15], 2
	v_lshlrev_b32_e32 v186, 4, v130
	s_lshl_b64 s[14:15], s[16:17], 2
	s_lshl_b64 s[16:17], s[18:19], 2
	s_lshl_b64 s[18:19], s[24:25], 2
	s_lshl_b64 s[20:21], s[22:23], 2
	s_lshl_b64 s[22:23], s[28:29], 2
	s_lshl_b64 s[24:25], s[56:57], 2
	s_lshl_b64 s[28:29], s[58:59], 2
	s_lshl_b64 s[30:31], s[30:31], 2
	s_lshl_b64 s[36:37], s[36:37], 2
	s_lshl_b64 s[38:39], s[38:39], 2
	s_lshl_b64 s[40:41], s[40:41], 2
	s_lshl_b64 s[42:43], s[42:43], 2
	s_lshl_b64 s[44:45], s[44:45], 2
	s_lshl_b64 s[46:47], s[46:47], 2
	s_lshl_b64 s[48:49], s[48:49], 2
	s_branch .LBB0_886

.LBB0_1049:
	s_or_b32 s33, s24, s72
	s_lshl_b32 s0, s33, 7
	s_or_b32 s68, s18, s0
	s_or_b32 s0, s33, s28
	s_ashr_i32 s1, s0, 31
	s_lshl_b64 s[0:1], s[0:1], 2
	s_add_u32 s0, s73, s0
	s_addc_u32 s1, s74, s1
	v_mov_b32_e32 v4, v0
	global_load_dword v211, v3, s[0:1]
	s_mov_b32 s69, s19
	s_waitcnt vmcnt(9)
	v_ashrrev_i32_e32 v70, 5, v4
	v_ashrrev_i32_e32 v71, 31, v70
	v_lshlrev_b32_e32 v2, 4, v4
	v_lshl_add_u64 v[6:7], s[68:69], 0, v[70:71]
	v_and_b32_e32 v2, 0x1f0, v2
	v_lshl_add_u64 v[8:9], s[20:21], 0, v[2:3]
	v_lshlrev_b64 v[6:7], 11, v[6:7]
	v_lshl_add_u64 v[62:63], v[8:9], 0, v[6:7]
	v_lshl_add_u64 v[10:11], s[36:37], 0, v[2:3]
	v_add_co_u32_e32 v14, vcc, s80, v62
	v_lshl_add_u64 v[64:65], v[10:11], 0, v[6:7]
	s_nop 0
	v_addc_co_u32_e32 v15, vcc, 0, v63, vcc
	v_add_co_u32_e32 v18, vcc, s80, v64
	global_load_dwordx4 v[6:9], v[62:63], off
	global_load_dwordx4 v[10:13], v[64:65], off
	v_addc_co_u32_e32 v19, vcc, 0, v65, vcc
	v_add_co_u32_e32 v22, vcc, s46, v62
	global_load_dwordx4 v[14:17], v[14:15], off
	s_nop 0
	global_load_dwordx4 v[18:21], v[18:19], off
	v_addc_co_u32_e32 v23, vcc, 0, v63, vcc
	v_add_co_u32_e32 v26, vcc, s46, v64
	s_movk_i32 s0, 0x210
	s_nop 0
	v_addc_co_u32_e32 v27, vcc, 0, v65, vcc
	v_add_co_u32_e32 v30, vcc, s81, v62
	global_load_dwordx4 v[22:25], v[22:23], off
	s_nop 0
	global_load_dwordx4 v[26:29], v[26:27], off
	v_addc_co_u32_e32 v31, vcc, 0, v63, vcc
	v_add_co_u32_e32 v34, vcc, s81, v64
	v_mul_lo_u32 v5, v70, s0
	s_nop 0
	v_addc_co_u32_e32 v35, vcc, 0, v65, vcc
	v_add_co_u32_e32 v38, vcc, s47, v62
	global_load_dwordx4 v[30:33], v[30:31], off
	s_nop 0
	global_load_dwordx4 v[34:37], v[34:35], off
	v_addc_co_u32_e32 v39, vcc, 0, v63, vcc
	v_add_co_u32_e32 v42, vcc, s47, v64
	v_add3_u32 v2, v5, v2, 0
	s_nop 0
	v_addc_co_u32_e32 v43, vcc, 0, v65, vcc
	v_add_co_u32_e32 v46, vcc, s82, v62
	global_load_dwordx4 v[38:41], v[38:39], off
	s_nop 0
	global_load_dwordx4 v[42:45], v[42:43], off
	v_addc_co_u32_e32 v47, vcc, 0, v63, vcc
	v_add_co_u32_e32 v50, vcc, s82, v64
	v_add_u32_e32 v5, 0x10800, v2
	s_nop 0
	v_addc_co_u32_e32 v51, vcc, 0, v65, vcc
	v_add_co_u32_e32 v54, vcc, s83, v62
	global_load_dwordx4 v[46:49], v[46:47], off
	s_nop 0
	global_load_dwordx4 v[50:53], v[50:51], off
	v_addc_co_u32_e32 v55, vcc, 0, v63, vcc
	v_add_co_u32_e32 v58, vcc, s83, v64
	s_cmp_lg_u32 s33, 0
	s_nop 0
	v_addc_co_u32_e32 v59, vcc, 0, v65, vcc
	v_add_co_u32_e32 v62, vcc, s84, v62
	global_load_dwordx4 v[54:57], v[54:55], off
	s_nop 0
	global_load_dwordx4 v[58:61], v[58:59], off
	v_addc_co_u32_e32 v63, vcc, 0, v63, vcc
	v_add_co_u32_e32 v66, vcc, s84, v64
	s_cselect_b64 s[24:25], -1, 0
	s_nop 0
	v_addc_co_u32_e32 v67, vcc, 0, v65, vcc
	global_load_dwordx4 v[62:65], v[62:63], off
	s_nop 0
	global_load_dwordx4 v[66:69], v[66:67], off
	s_cmp_eq_u32 s33, 0
	s_cbranch_scc1 .Lmy_p4_noct
	s_or_b32 s0, s33, s29
	s_ashr_i32 s1, s0, 31
	s_lshl_b64 s[0:1], s[0:1], 17
	s_add_u32 s0, s75, s0
	s_addc_u32 s1, s76, s1
	v_and_b32_e32 v216, 63, v4
	v_lshlrev_b32_e32 v216, 4, v216
	v_mov_b32_e32 v217, 0
	v_lshl_add_u64 v[218:219], s[0:1], 0, v[216:217]
	v_lshl_add_u64 v[218:219], v[218:219], 0, s[38:39]
	s_movk_i32 s0, 0x1000
	v_add_co_u32_e32 v220, vcc, s0, v218
	global_load_dwordx4 v[84:87], v[218:219], off
	global_load_dwordx4 v[88:91], v[218:219], off offset:1024
	global_load_dwordx4 v[92:95], v[218:219], off offset:2048
	global_load_dwordx4 v[96:99], v[218:219], off offset:3072
	v_addc_co_u32_e32 v221, vcc, 0, v219, vcc
	global_load_dwordx4 v[100:103], v[220:221], off
	global_load_dwordx4 v[104:107], v[220:221], off offset:1024
	global_load_dwordx4 v[108:111], v[220:221], off offset:2048
	global_load_dwordx4 v[112:115], v[220:221], off offset:3072
	v_add_co_u32_e32 v220, vcc, 0x2000, v218
	s_nop 1
	v_addc_co_u32_e32 v221, vcc, 0, v219, vcc
	v_add_co_u32_e32 v218, vcc, 0x3000, v218
	global_load_dwordx4 v[116:119], v[220:221], off
	global_load_dwordx4 v[120:123], v[220:221], off offset:1024
	global_load_dwordx4 v[124:127], v[220:221], off offset:2048
	global_load_dwordx4 v[128:131], v[220:221], off offset:3072
	v_addc_co_u32_e32 v219, vcc, 0, v219, vcc
	global_load_dwordx4 v[132:135], v[218:219], off
	global_load_dwordx4 v[136:139], v[218:219], off offset:1024
	global_load_dwordx4 v[140:143], v[218:219], off offset:2048
	global_load_dwordx4 v[144:147], v[218:219], off offset:3072

.LBB0_1181:
	s_add_u32 s2, s96, 0x2400000
	s_barrier
	s_addc_u32 s3, s97, 0
	v_readfirstlane_b32 s9, v0
	s_ashr_i32 s5, s9, 6
	s_ashr_i32 s10, s9, 8
	s_and_b32 s1, s5, 3
	v_and_b32_e32 v1, 15, v0
	s_lshl_b32 s0, s4, 8
	s_lshl_b32 s11, s1, 5
	v_lshl_or_b32 v178, s10, 6, v1
	s_lshl_b32 s12, s8, 8
	s_or_b32 s0, s11, s0
	v_lshrrev_b32_e32 v130, 2, v0
	v_add_u32_e32 v168, s12, v178
	v_and_or_b32 v130, v130, 12, s0
	v_ashrrev_i32_e32 v169, 31, v168
	v_ashrrev_i32_e32 v131, 31, v130
	v_lshlrev_b64 v[132:133], 11, v[168:169]
	v_lshl_add_u64 v[134:135], s[2:3], 0, v[132:133]
	v_lshlrev_b64 v[132:133], 1, v[130:131]
	v_lshl_add_u64 v[134:135], v[134:135], 0, v[132:133]
	global_load_dwordx2 v[182:183], v[134:135], off
	global_load_dwordx2 v[184:185], v[134:135], off offset:32
	global_load_dwordx2 v[186:187], v[134:135], off offset:256
	global_load_dwordx2 v[180:181], v[134:135], off offset:288
	v_or_b32_e32 v166, 16, v168
	v_ashrrev_i32_e32 v167, 31, v166
	s_mov_b32 s0, 0x3f9837f0
	v_or_b32_e32 v162, 32, v168
	v_ashrrev_i32_e32 v163, 31, v162
	v_or_b32_e32 v164, 48, v168
	v_ashrrev_i32_e32 v165, 31, v164
	v_add_u32_e32 v170, 0x80, v168
	v_ashrrev_i32_e32 v171, 31, v170
	v_add_u32_e32 v172, 0x90, v168
	v_ashrrev_i32_e32 v173, 31, v172
	v_add_u32_e32 v174, 0xa0, v168
	v_ashrrev_i32_e32 v175, 31, v174
	v_add_u32_e32 v176, 0xb0, v168
	v_ashrrev_i32_e32 v177, 31, v176
	v_lshlrev_b64 v[142:143], 11, v[166:167]
	v_lshl_add_u64 v[142:143], s[2:3], 0, v[142:143]
	v_lshl_add_u64 v[142:143], v[142:143], 0, v[132:133]
	global_load_dwordx2 v[188:189], v[142:143], off
	global_load_dwordx2 v[190:191], v[142:143], off offset:32
	global_load_dwordx2 v[192:193], v[142:143], off offset:256
	global_load_dwordx2 v[194:195], v[142:143], off offset:288
	v_lshlrev_b64 v[142:143], 11, v[162:163]
	v_lshl_add_u64 v[142:143], s[2:3], 0, v[142:143]
	v_lshl_add_u64 v[142:143], v[142:143], 0, v[132:133]
	global_load_dwordx2 v[196:197], v[142:143], off
	global_load_dwordx2 v[198:199], v[142:143], off offset:32
	global_load_dwordx2 v[200:201], v[142:143], off offset:256
	global_load_dwordx2 v[202:203], v[142:143], off offset:288
	v_lshlrev_b64 v[142:143], 11, v[164:165]
	v_lshl_add_u64 v[142:143], s[2:3], 0, v[142:143]
	v_lshl_add_u64 v[142:143], v[142:143], 0, v[132:133]
	global_load_dwordx2 v[204:205], v[142:143], off
	global_load_dwordx2 v[206:207], v[142:143], off offset:32
	global_load_dwordx2 v[208:209], v[142:143], off offset:256
	global_load_dwordx2 v[210:211], v[142:143], off offset:288
	v_lshlrev_b64 v[142:143], 11, v[170:171]
	v_lshl_add_u64 v[142:143], s[2:3], 0, v[142:143]
	v_lshl_add_u64 v[142:143], v[142:143], 0, v[132:133]
	global_load_dwordx2 v[212:213], v[142:143], off
	global_load_dwordx2 v[214:215], v[142:143], off offset:32
	global_load_dwordx2 v[216:217], v[142:143], off offset:256
	global_load_dwordx2 v[218:219], v[142:143], off offset:288
	v_lshlrev_b64 v[142:143], 11, v[172:173]
	v_lshl_add_u64 v[142:143], s[2:3], 0, v[142:143]
	v_lshl_add_u64 v[142:143], v[142:143], 0, v[132:133]
	global_load_dwordx2 v[220:221], v[142:143], off
	global_load_dwordx2 v[222:223], v[142:143], off offset:32
	global_load_dwordx2 v[224:225], v[142:143], off offset:256
	global_load_dwordx2 v[226:227], v[142:143], off offset:288
	v_lshlrev_b64 v[142:143], 11, v[174:175]
	v_lshl_add_u64 v[142:143], s[2:3], 0, v[142:143]
	v_lshl_add_u64 v[142:143], v[142:143], 0, v[132:133]
	global_load_dwordx2 v[228:229], v[142:143], off
	global_load_dwordx2 v[230:231], v[142:143], off offset:32
	global_load_dwordx2 v[232:233], v[142:143], off offset:256
	global_load_dwordx2 v[234:235], v[142:143], off offset:288
	v_lshlrev_b64 v[142:143], 11, v[176:177]
	v_lshl_add_u64 v[142:143], s[2:3], 0, v[142:143]
	v_lshl_add_u64 v[142:143], v[142:143], 0, v[132:133]
	global_load_dwordx2 v[236:237], v[142:143], off
	global_load_dwordx2 v[238:239], v[142:143], off offset:32
	global_load_dwordx2 v[240:241], v[142:143], off offset:256
	global_load_dwordx2 v[242:243], v[142:143], off offset:288
	s_waitcnt vmcnt(28)
	v_lshlrev_b32_e32 v144, 16, v182
	v_and_b32_e32 v145, 0xffff0000, v182
	v_lshlrev_b32_e32 v182, 16, v183
	v_and_b32_e32 v183, 0xffff0000, v183
	v_lshlrev_b32_e32 v146, 16, v184
	v_and_b32_e32 v147, 0xffff0000, v184
	v_lshlrev_b32_e32 v184, 16, v185
	v_and_b32_e32 v185, 0xffff0000, v185
	v_lshlrev_b32_e32 v148, 16, v186
	v_and_b32_e32 v149, 0xffff0000, v186
	v_lshlrev_b32_e32 v186, 16, v187
	v_and_b32_e32 v187, 0xffff0000, v187
	v_lshlrev_b32_e32 v150, 16, v180
	v_and_b32_e32 v151, 0xffff0000, v180
	v_lshlrev_b32_e32 v180, 16, v181
	v_and_b32_e32 v181, 0xffff0000, v181
	v_pk_fma_f32 v[88:89], v[182:183], s[0:1], v[88:89] op_sel_hi:[1,0,1]
	v_pk_fma_f32 v[86:87], v[144:145], s[0:1], v[86:87] op_sel_hi:[1,0,1]
	v_pk_fma_f32 v[84:85], v[184:185], s[0:1], v[84:85] op_sel_hi:[1,0,1]
	v_pk_fma_f32 v[82:83], v[146:147], s[0:1], v[82:83] op_sel_hi:[1,0,1]
	v_pk_fma_f32 v[80:81], v[186:187], s[0:1], v[80:81] op_sel_hi:[1,0,1]
	v_pk_fma_f32 v[78:79], v[148:149], s[0:1], v[78:79] op_sel_hi:[1,0,1]
	v_pk_fma_f32 v[76:77], v[180:181], s[0:1], v[76:77] op_sel_hi:[1,0,1]
	v_pk_fma_f32 v[74:75], v[150:151], s[0:1], v[74:75] op_sel_hi:[1,0,1]
	s_nop 0
	s_waitcnt vmcnt(27)
	v_lshlrev_b32_e32 v144, 16, v188
	v_and_b32_e32 v145, 0xffff0000, v188
	v_lshlrev_b32_e32 v188, 16, v189
	v_and_b32_e32 v189, 0xffff0000, v189
	s_waitcnt vmcnt(26)
	v_lshlrev_b32_e32 v146, 16, v190
	v_and_b32_e32 v147, 0xffff0000, v190
	v_lshlrev_b32_e32 v190, 16, v191
	v_and_b32_e32 v191, 0xffff0000, v191
	s_waitcnt vmcnt(25)
	v_lshlrev_b32_e32 v148, 16, v192
	v_and_b32_e32 v149, 0xffff0000, v192
	v_lshlrev_b32_e32 v192, 16, v193
	v_and_b32_e32 v193, 0xffff0000, v193
	s_waitcnt vmcnt(24)
	v_lshlrev_b32_e32 v150, 16, v194
	v_and_b32_e32 v151, 0xffff0000, v194
	v_lshlrev_b32_e32 v194, 16, v195
	v_and_b32_e32 v195, 0xffff0000, v195
	v_pk_fma_f32 v[128:129], v[188:189], s[0:1], v[128:129] op_sel_hi:[1,0,1]
	v_pk_fma_f32 v[126:127], v[144:145], s[0:1], v[126:127] op_sel_hi:[1,0,1]
	v_pk_fma_f32 v[112:113], v[190:191], s[0:1], v[112:113] op_sel_hi:[1,0,1]
	v_pk_fma_f32 v[110:111], v[146:147], s[0:1], v[110:111] op_sel_hi:[1,0,1]
	v_pk_fma_f32 v[104:105], v[192:193], s[0:1], v[104:105] op_sel_hi:[1,0,1]
	v_pk_fma_f32 v[102:103], v[148:149], s[0:1], v[102:103] op_sel_hi:[1,0,1]
	v_pk_fma_f32 v[92:93], v[194:195], s[0:1], v[92:93] op_sel_hi:[1,0,1]
	v_pk_fma_f32 v[90:91], v[150:151], s[0:1], v[90:91] op_sel_hi:[1,0,1]
	s_nop 0
	s_waitcnt vmcnt(23)
	v_lshlrev_b32_e32 v144, 16, v196
	v_and_b32_e32 v145, 0xffff0000, v196
	v_lshlrev_b32_e32 v196, 16, v197
	v_and_b32_e32 v197, 0xffff0000, v197
	s_waitcnt vmcnt(22)
	v_lshlrev_b32_e32 v146, 16, v198
	v_and_b32_e32 v147, 0xffff0000, v198
	v_lshlrev_b32_e32 v198, 16, v199
	v_and_b32_e32 v199, 0xffff0000, v199
	s_waitcnt vmcnt(21)
	v_lshlrev_b32_e32 v148, 16, v200
	v_and_b32_e32 v149, 0xffff0000, v200
	v_lshlrev_b32_e32 v200, 16, v201
	v_and_b32_e32 v201, 0xffff0000, v201
	s_waitcnt vmcnt(20)
	v_lshlrev_b32_e32 v150, 16, v202
	v_and_b32_e32 v151, 0xffff0000, v202
	v_lshlrev_b32_e32 v202, 16, v203
	v_and_b32_e32 v203, 0xffff0000, v203
	v_pk_fma_f32 v[124:125], v[196:197], s[0:1], v[124:125] op_sel_hi:[1,0,1]
	v_pk_fma_f32 v[122:123], v[144:145], s[0:1], v[122:123] op_sel_hi:[1,0,1]
	v_pk_fma_f32 v[120:121], v[198:199], s[0:1], v[120:121] op_sel_hi:[1,0,1]
	v_pk_fma_f32 v[118:119], v[146:147], s[0:1], v[118:119] op_sel_hi:[1,0,1]
	v_pk_fma_f32 v[116:117], v[200:201], s[0:1], v[116:117] op_sel_hi:[1,0,1]
	v_pk_fma_f32 v[114:115], v[148:149], s[0:1], v[114:115] op_sel_hi:[1,0,1]
	v_pk_fma_f32 v[108:109], v[202:203], s[0:1], v[108:109] op_sel_hi:[1,0,1]
	v_pk_fma_f32 v[106:107], v[150:151], s[0:1], v[106:107] op_sel_hi:[1,0,1]
	s_nop 0
	s_waitcnt vmcnt(19)
	v_lshlrev_b32_e32 v144, 16, v204
	v_and_b32_e32 v145, 0xffff0000, v204
	v_lshlrev_b32_e32 v204, 16, v205
	v_and_b32_e32 v205, 0xffff0000, v205
	s_waitcnt vmcnt(18)
	v_lshlrev_b32_e32 v146, 16, v206
	v_and_b32_e32 v147, 0xffff0000, v206
	v_lshlrev_b32_e32 v206, 16, v207
	v_and_b32_e32 v207, 0xffff0000, v207
	s_waitcnt vmcnt(17)
	v_lshlrev_b32_e32 v148, 16, v208
	v_and_b32_e32 v149, 0xffff0000, v208
	v_lshlrev_b32_e32 v208, 16, v209
	v_and_b32_e32 v209, 0xffff0000, v209
	s_waitcnt vmcnt(16)
	v_lshlrev_b32_e32 v150, 16, v210
	v_and_b32_e32 v151, 0xffff0000, v210
	v_lshlrev_b32_e32 v210, 16, v211
	v_and_b32_e32 v211, 0xffff0000, v211
	v_pk_fma_f32 v[100:101], v[204:205], s[0:1], v[100:101] op_sel_hi:[1,0,1]
	v_pk_fma_f32 v[98:99], v[144:145], s[0:1], v[98:99] op_sel_hi:[1,0,1]
	v_pk_fma_f32 v[96:97], v[206:207], s[0:1], v[96:97] op_sel_hi:[1,0,1]
	v_pk_fma_f32 v[94:95], v[146:147], s[0:1], v[94:95] op_sel_hi:[1,0,1]
	v_pk_fma_f32 v[72:73], v[208:209], s[0:1], v[72:73] op_sel_hi:[1,0,1]
	v_pk_fma_f32 v[70:71], v[148:149], s[0:1], v[70:71] op_sel_hi:[1,0,1]
	v_pk_fma_f32 v[68:69], v[210:211], s[0:1], v[68:69] op_sel_hi:[1,0,1]
	v_pk_fma_f32 v[66:67], v[150:151], s[0:1], v[66:67] op_sel_hi:[1,0,1]
	s_nop 0
	s_waitcnt vmcnt(15)
	v_lshlrev_b32_e32 v144, 16, v212
	v_and_b32_e32 v145, 0xffff0000, v212
	v_lshlrev_b32_e32 v212, 16, v213
	v_and_b32_e32 v213, 0xffff0000, v213
	s_waitcnt vmcnt(14)
	v_lshlrev_b32_e32 v146, 16, v214
	v_and_b32_e32 v147, 0xffff0000, v214
	v_lshlrev_b32_e32 v214, 16, v215
	v_and_b32_e32 v215, 0xffff0000, v215
	s_waitcnt vmcnt(13)
	v_lshlrev_b32_e32 v148, 16, v216
	v_and_b32_e32 v149, 0xffff0000, v216
	v_lshlrev_b32_e32 v216, 16, v217
	v_and_b32_e32 v217, 0xffff0000, v217
	s_waitcnt vmcnt(12)
	v_lshlrev_b32_e32 v150, 16, v218
	v_and_b32_e32 v151, 0xffff0000, v218
	v_lshlrev_b32_e32 v218, 16, v219
	v_and_b32_e32 v219, 0xffff0000, v219
	v_pk_fma_f32 v[64:65], v[212:213], s[0:1], v[64:65] op_sel_hi:[1,0,1]
	v_pk_fma_f32 v[62:63], v[144:145], s[0:1], v[62:63] op_sel_hi:[1,0,1]
	v_pk_fma_f32 v[60:61], v[214:215], s[0:1], v[60:61] op_sel_hi:[1,0,1]
	v_pk_fma_f32 v[58:59], v[146:147], s[0:1], v[58:59] op_sel_hi:[1,0,1]
	v_pk_fma_f32 v[56:57], v[216:217], s[0:1], v[56:57] op_sel_hi:[1,0,1]
	v_pk_fma_f32 v[54:55], v[148:149], s[0:1], v[54:55] op_sel_hi:[1,0,1]
	v_pk_fma_f32 v[52:53], v[218:219], s[0:1], v[52:53] op_sel_hi:[1,0,1]
	v_pk_fma_f32 v[50:51], v[150:151], s[0:1], v[50:51] op_sel_hi:[1,0,1]
	s_nop 0
	s_waitcnt vmcnt(11)
	v_lshlrev_b32_e32 v144, 16, v220
	v_and_b32_e32 v145, 0xffff0000, v220
	v_lshlrev_b32_e32 v220, 16, v221
	v_and_b32_e32 v221, 0xffff0000, v221
	s_waitcnt vmcnt(10)
	v_lshlrev_b32_e32 v146, 16, v222
	v_and_b32_e32 v147, 0xffff0000, v222
	v_lshlrev_b32_e32 v222, 16, v223
	v_and_b32_e32 v223, 0xffff0000, v223
	s_waitcnt vmcnt(9)
	v_lshlrev_b32_e32 v148, 16, v224
	v_and_b32_e32 v149, 0xffff0000, v224
	v_lshlrev_b32_e32 v224, 16, v225
	v_and_b32_e32 v225, 0xffff0000, v225
	s_waitcnt vmcnt(8)
	v_lshlrev_b32_e32 v150, 16, v226
	v_and_b32_e32 v151, 0xffff0000, v226
	v_lshlrev_b32_e32 v226, 16, v227
	v_and_b32_e32 v227, 0xffff0000, v227
	v_pk_fma_f32 v[48:49], v[220:221], s[0:1], v[48:49] op_sel_hi:[1,0,1]
	v_pk_fma_f32 v[46:47], v[144:145], s[0:1], v[46:47] op_sel_hi:[1,0,1]
	v_pk_fma_f32 v[44:45], v[222:223], s[0:1], v[44:45] op_sel_hi:[1,0,1]
	v_pk_fma_f32 v[42:43], v[146:147], s[0:1], v[42:43] op_sel_hi:[1,0,1]
	v_pk_fma_f32 v[40:41], v[224:225], s[0:1], v[40:41] op_sel_hi:[1,0,1]
	v_pk_fma_f32 v[38:39], v[148:149], s[0:1], v[38:39] op_sel_hi:[1,0,1]
	v_pk_fma_f32 v[36:37], v[226:227], s[0:1], v[36:37] op_sel_hi:[1,0,1]
	v_pk_fma_f32 v[34:35], v[150:151], s[0:1], v[34:35] op_sel_hi:[1,0,1]
	s_nop 0
	s_waitcnt vmcnt(7)
	v_lshlrev_b32_e32 v132, 16, v228
	v_and_b32_e32 v133, 0xffff0000, v228
	v_lshlrev_b32_e32 v228, 16, v229
	v_and_b32_e32 v229, 0xffff0000, v229
	s_waitcnt vmcnt(6)
	v_lshlrev_b32_e32 v144, 16, v230
	v_and_b32_e32 v145, 0xffff0000, v230
	v_lshlrev_b32_e32 v230, 16, v231
	v_and_b32_e32 v231, 0xffff0000, v231
	s_waitcnt vmcnt(5)
	v_lshlrev_b32_e32 v146, 16, v232
	v_and_b32_e32 v147, 0xffff0000, v232
	v_lshlrev_b32_e32 v232, 16, v233
	v_and_b32_e32 v233, 0xffff0000, v233
	s_waitcnt vmcnt(4)
	v_lshlrev_b32_e32 v148, 16, v234
	v_and_b32_e32 v149, 0xffff0000, v234
	v_lshlrev_b32_e32 v234, 16, v235
	v_and_b32_e32 v235, 0xffff0000, v235
	v_pk_fma_f32 v[32:33], v[228:229], s[0:1], v[32:33] op_sel_hi:[1,0,1]
	v_pk_fma_f32 v[30:31], v[132:133], s[0:1], v[30:31] op_sel_hi:[1,0,1]
	v_pk_fma_f32 v[28:29], v[230:231], s[0:1], v[28:29] op_sel_hi:[1,0,1]
	v_pk_fma_f32 v[26:27], v[144:145], s[0:1], v[26:27] op_sel_hi:[1,0,1]
	v_pk_fma_f32 v[24:25], v[232:233], s[0:1], v[24:25] op_sel_hi:[1,0,1]
	v_pk_fma_f32 v[22:23], v[146:147], s[0:1], v[22:23] op_sel_hi:[1,0,1]
	v_pk_fma_f32 v[20:21], v[234:235], s[0:1], v[20:21] op_sel_hi:[1,0,1]
	v_pk_fma_f32 v[18:19], v[148:149], s[0:1], v[18:19] op_sel_hi:[1,0,1]
	v_add_f32_e32 v133, v86, v87
	v_add_f32_e32 v142, v88, v89
	v_add_f32_e32 v143, v82, v83
	v_add_f32_e32 v144, v84, v85
	v_add_f32_e32 v133, v133, v142
	v_add_f32_e32 v145, v78, v79
	v_add_f32_e32 v146, v80, v81
	v_add_f32_e32 v142, v143, v144
	v_add_f32_e32 v133, 0, v133
	v_add_f32_e32 v147, v74, v75
	v_add_f32_e32 v148, v76, v77
	v_add_f32_e32 v143, v145, v146
	v_add_f32_e32 v133, v142, v133
	v_add_f32_e32 v144, v147, v148
	v_add_f32_e32 v133, v143, v133
	v_add_f32_e32 v133, v144, v133
	v_mov_b32_e32 v142, v133
	s_nop 1
	v_permlane16_swap_b32_e32 v133, v142
	v_add_f32_e32 v133, v133, v142
	v_mov_b32_e32 v142, v133
	s_nop 1
	v_permlane32_swap_b32_e32 v133, v142
	v_add_f32_e32 v133, v133, v142
	v_fmamk_f32 v143, v133, 0xbc800000, v89
	v_fmamk_f32 v145, v133, 0xbc800000, v87
	v_fmamk_f32 v147, v133, 0xbc800000, v85
	v_fmamk_f32 v149, v133, 0xbc800000, v83
	v_fmamk_f32 v142, v133, 0xbc800000, v88
	v_fmamk_f32 v144, v133, 0xbc800000, v86
	v_fmamk_f32 v146, v133, 0xbc800000, v84
	v_fmamk_f32 v148, v133, 0xbc800000, v82
	v_fmamk_f32 v151, v133, 0xbc800000, v81
	v_fmamk_f32 v153, v133, 0xbc800000, v79
	v_mul_f32_e32 v145, v145, v145
	v_mul_f32_e32 v143, v143, v143
	v_mul_f32_e32 v149, v149, v149
	v_mul_f32_e32 v147, v147, v147
	v_fmamk_f32 v150, v133, 0xbc800000, v80
	v_fmamk_f32 v152, v133, 0xbc800000, v78
	v_fmamk_f32 v155, v133, 0xbc800000, v77
	v_fmamk_f32 v157, v133, 0xbc800000, v75
	v_mul_f32_e32 v153, v153, v153
	v_mul_f32_e32 v151, v151, v151
	v_fmac_f32_e32 v145, v144, v144
	v_fmac_f32_e32 v143, v142, v142
	v_fmac_f32_e32 v149, v148, v148
	v_fmac_f32_e32 v147, v146, v146
	v_fmamk_f32 v154, v133, 0xbc800000, v76
	v_fmamk_f32 v156, v133, 0xbc800000, v74
	v_mul_f32_e32 v157, v157, v157
	v_mul_f32_e32 v155, v155, v155
	v_fmac_f32_e32 v153, v152, v152
	v_fmac_f32_e32 v151, v150, v150
	v_add_f32_e32 v142, v145, v143
	v_add_f32_e32 v143, v149, v147
	v_fmac_f32_e32 v157, v156, v156
	v_fmac_f32_e32 v155, v154, v154
	v_add_f32_e32 v144, v153, v151
	v_add_f32_e32 v142, v142, v143
	v_add_f32_e32 v145, v157, v155
	v_add_f32_e32 v142, v144, v142
	v_add_f32_e32 v150, v145, v142
	s_lshl_b32 s1, s1, 3
	v_mov_b32_e32 v151, v150
	s_nop 1
	v_permlane16_swap_b32_e32 v150, v151
	v_and_b32_e32 v132, 63, v0
	v_cmp_gt_u32_e32 vcc, 16, v132
	s_add_i32 s2, s1, 0
	s_waitcnt vmcnt(3)
	v_lshlrev_b32_e32 v142, 16, v236
	v_and_b32_e32 v143, 0xffff0000, v236
	v_lshlrev_b32_e32 v236, 16, v237
	v_and_b32_e32 v237, 0xffff0000, v237
	s_waitcnt vmcnt(2)
	v_lshlrev_b32_e32 v144, 16, v238
	v_and_b32_e32 v145, 0xffff0000, v238
	v_lshlrev_b32_e32 v238, 16, v239
	v_and_b32_e32 v239, 0xffff0000, v239
	s_waitcnt vmcnt(1)
	v_lshlrev_b32_e32 v146, 16, v240
	v_and_b32_e32 v147, 0xffff0000, v240
	v_lshlrev_b32_e32 v240, 16, v241
	v_and_b32_e32 v241, 0xffff0000, v241
	s_waitcnt vmcnt(0)
	v_lshlrev_b32_e32 v148, 16, v242
	v_and_b32_e32 v149, 0xffff0000, v242
	v_lshlrev_b32_e32 v242, 16, v243
	v_and_b32_e32 v243, 0xffff0000, v243
	v_pk_fma_f32 v[16:17], v[236:237], s[0:1], v[16:17] op_sel_hi:[1,0,1]
	v_pk_fma_f32 v[14:15], v[142:143], s[0:1], v[14:15] op_sel_hi:[1,0,1]
	v_pk_fma_f32 v[12:13], v[238:239], s[0:1], v[12:13] op_sel_hi:[1,0,1]
	v_pk_fma_f32 v[10:11], v[144:145], s[0:1], v[10:11] op_sel_hi:[1,0,1]
	v_pk_fma_f32 v[8:9], v[240:241], s[0:1], v[8:9] op_sel_hi:[1,0,1]
	v_pk_fma_f32 v[6:7], v[146:147], s[0:1], v[6:7] op_sel_hi:[1,0,1]
	v_pk_fma_f32 v[4:5], v[242:243], s[0:1], v[4:5] op_sel_hi:[1,0,1]
	v_lshlrev_b64 v[224:225], 2, v[130:131]
	v_lshl_add_u64 v[226:227], s[54:55], 0, v[224:225]
	v_lshl_add_u64 v[224:225], s[56:57], 0, v[224:225]
	global_load_dwordx4 v[192:195], v[224:225], off
	global_load_dwordx4 v[196:199], v[226:227], off
	global_load_dwordx4 v[200:203], v[226:227], off offset:64
	global_load_dwordx4 v[204:207], v[224:225], off offset:64
	global_load_dwordx4 v[208:211], v[224:225], off offset:512
	global_load_dwordx4 v[212:215], v[226:227], off offset:512
	global_load_dwordx4 v[216:219], v[226:227], off offset:576
	global_load_dwordx4 v[220:223], v[224:225], off offset:576
	v_pk_fma_f32 v[2:3], v[148:149], s[0:1], v[2:3] op_sel_hi:[1,0,1]
	v_add_f32_e32 v134, v150, v151
	v_mov_b32_e32 v135, v134
	s_nop 1
	v_permlane32_swap_b32_e32 v134, v135
	s_and_saveexec_b64 s[0:1], vcc
	s_cbranch_execz .LBB0_1183
	s_lshl_b32 s3, s10, 11
	s_add_i32 s3, s2, s3
	v_mul_f32_e32 v136, 0x3c800000, v133
	v_lshl_add_u32 v133, v1, 5, s3
	v_add_f32_e32 v137, v134, v135
	ds_write_b64 v133, v[136:137]

.LBB0_1221:
	s_or_b64 exec, exec, s[2:3]
	v_lshlrev_b64 v[0:1], 2, v[130:131]
	s_waitcnt lgkmcnt(0)
	s_barrier
	v_lshl_add_u64 v[130:131], s[54:55], 0, v[0:1]
	v_lshl_add_u64 v[134:135], s[56:57], 0, v[0:1]
	v_mov_b32_e32 v154, v192
	v_mov_b32_e32 v155, v193
	v_mov_b32_e32 v156, v194
	v_mov_b32_e32 v157, v195
	v_mov_b32_e32 v158, v196
	v_mov_b32_e32 v159, v197
	v_mov_b32_e32 v160, v198
	v_mov_b32_e32 v161, v199
	v_mov_b32_e32 v146, v200
	v_mov_b32_e32 v147, v201
	v_mov_b32_e32 v148, v202
	v_mov_b32_e32 v149, v203
	v_mov_b32_e32 v150, v204
	v_mov_b32_e32 v151, v205
	v_mov_b32_e32 v152, v206
	v_mov_b32_e32 v153, v207
	v_mov_b32_e32 v138, v208
	v_mov_b32_e32 v139, v209
	v_mov_b32_e32 v140, v210
	v_mov_b32_e32 v141, v211
	v_mov_b32_e32 v142, v212
	v_mov_b32_e32 v143, v213
	v_mov_b32_e32 v144, v214
	v_mov_b32_e32 v145, v215
	s_nop 0
	v_mov_b32_e32 v130, v216
	v_mov_b32_e32 v131, v217
	v_mov_b32_e32 v132, v218
	v_mov_b32_e32 v133, v219
	s_nop 0
	v_mov_b32_e32 v134, v220
	v_mov_b32_e32 v135, v221
	v_mov_b32_e32 v136, v222
	v_mov_b32_e32 v137, v223
	v_lshl_add_u32 v178, v178, 3, 0
	v_lshlrev_b64 v[182:183], 12, v[168:169]
	v_add_u32_e32 v169, 0x2000, v178
	s_waitcnt lgkmcnt(0)
	v_cmp_ne_u32_e32 vcc, 0, v179
	ds_read2_b64 v[178:181], v169 offset1:16
	v_mov_b32_e32 v168, 0x7fc00000
	v_lshl_add_u64 v[182:183], s[58:59], 0, v[182:183]
	s_or_b64 vcc, vcc, s[6:7]
	v_lshlrev_b64 v[166:167], 12, v[166:167]
	s_waitcnt lgkmcnt(0)
	v_sub_f32_e32 v87, v87, v178
	v_sub_f32_e32 v86, v86, v178
	v_sub_f32_e32 v89, v89, v178
	v_sub_f32_e32 v88, v88, v178
	v_sub_f32_e32 v83, v83, v178
	v_sub_f32_e32 v82, v82, v178
	v_sub_f32_e32 v85, v85, v178
	v_sub_f32_e32 v84, v84, v178
	v_sub_f32_e32 v79, v79, v178
	v_sub_f32_e32 v78, v78, v178
	v_sub_f32_e32 v81, v81, v178
	v_sub_f32_e32 v80, v80, v178
	v_sub_f32_e32 v75, v75, v178
	v_sub_f32_e32 v74, v74, v178
	v_sub_f32_e32 v77, v77, v178
	v_sub_f32_e32 v76, v76, v178
	v_pk_mul_f32 v[88:89], v[178:179], v[88:89] op_sel:[1,0]
	v_pk_mul_f32 v[86:87], v[178:179], v[86:87] op_sel:[1,0]
	v_pk_mul_f32 v[84:85], v[178:179], v[84:85] op_sel:[1,0]
	v_pk_mul_f32 v[82:83], v[178:179], v[82:83] op_sel:[1,0]
	v_pk_mul_f32 v[80:81], v[178:179], v[80:81] op_sel:[1,0]
	v_pk_mul_f32 v[78:79], v[178:179], v[78:79] op_sel:[1,0]
	v_pk_mul_f32 v[76:77], v[178:179], v[76:77] op_sel:[1,0]
	v_pk_mul_f32 v[74:75], v[178:179], v[74:75] op_sel:[1,0]
	v_lshl_add_u64 v[182:183], v[182:183], 0, v[0:1]
	v_sub_f32_e32 v127, v127, v180
	v_sub_f32_e32 v126, v126, v180
	v_sub_f32_e32 v129, v129, v180
	v_sub_f32_e32 v128, v128, v180
	v_pk_mul_f32 v[128:129], v[180:181], v[128:129] op_sel:[1,0]
	v_pk_mul_f32 v[126:127], v[180:181], v[126:127] op_sel:[1,0]
	v_pk_fma_f32 v[86:87], v[158:159], v[86:87], v[154:155]
	v_pk_fma_f32 v[88:89], v[160:161], v[88:89], v[156:157]
	v_pk_fma_f32 v[82:83], v[146:147], v[82:83], v[150:151]
	v_pk_fma_f32 v[84:85], v[148:149], v[84:85], v[152:153]
	v_pk_fma_f32 v[178:179], v[142:143], v[78:79], v[138:139]
	v_pk_fma_f32 v[184:185], v[144:145], v[80:81], v[140:141]
	v_pk_fma_f32 v[186:187], v[130:131], v[74:75], v[134:135]
	v_pk_fma_f32 v[188:189], v[132:133], v[76:77], v[136:137]
	v_cndmask_b32_e32 v77, v89, v168, vcc
	v_cndmask_b32_e32 v76, v88, v168, vcc
	v_cndmask_b32_e32 v75, v87, v168, vcc
	v_cndmask_b32_e32 v74, v86, v168, vcc
	v_cndmask_b32_e32 v81, v85, v168, vcc
	v_cndmask_b32_e32 v80, v84, v168, vcc
	v_cndmask_b32_e32 v79, v83, v168, vcc
	v_cndmask_b32_e32 v78, v82, v168, vcc
	v_cndmask_b32_e32 v85, v185, v168, vcc
	v_cndmask_b32_e32 v84, v184, v168, vcc
	v_cndmask_b32_e32 v83, v179, v168, vcc
	v_cndmask_b32_e32 v82, v178, v168, vcc
	v_cndmask_b32_e32 v89, v189, v168, vcc
	v_cndmask_b32_e32 v88, v188, v168, vcc
	v_cndmask_b32_e32 v87, v187, v168, vcc
	v_cndmask_b32_e32 v86, v186, v168, vcc
	global_store_dwordx4 v[182:183], v[74:77], off
	global_store_dwordx4 v[182:183], v[78:81], off offset:64
	global_store_dwordx4 v[182:183], v[82:85], off offset:512
	global_store_dwordx4 v[182:183], v[86:89], off offset:576
	v_lshl_add_u64 v[74:75], s[58:59], 0, v[166:167]
	v_lshl_add_u64 v[82:83], v[74:75], 0, v[0:1]
	v_sub_f32_e32 v75, v111, v180
	v_sub_f32_e32 v74, v110, v180
	v_sub_f32_e32 v77, v113, v180
	v_sub_f32_e32 v76, v112, v180
	v_pk_mul_f32 v[76:77], v[180:181], v[76:77] op_sel:[1,0]
	v_pk_mul_f32 v[74:75], v[180:181], v[74:75] op_sel:[1,0]
	v_pk_fma_f32 v[76:77], v[148:149], v[76:77], v[152:153]
	v_pk_fma_f32 v[74:75], v[146:147], v[74:75], v[150:151]
	v_cndmask_b32_e32 v77, v77, v168, vcc
	v_cndmask_b32_e32 v76, v76, v168, vcc
	v_cndmask_b32_e32 v75, v75, v168, vcc
	v_cndmask_b32_e32 v74, v74, v168, vcc
	global_store_dwordx4 v[82:83], v[74:77], off offset:64
	ds_read2_b64 v[78:81], v169 offset0:32 offset1:48
	v_pk_fma_f32 v[126:127], v[158:159], v[126:127], v[154:155]
	v_sub_f32_e32 v75, v103, v180
	v_sub_f32_e32 v74, v102, v180
	v_sub_f32_e32 v77, v105, v180
	v_sub_f32_e32 v76, v104, v180
	v_pk_mul_f32 v[76:77], v[180:181], v[76:77] op_sel:[1,0]
	v_pk_mul_f32 v[74:75], v[180:181], v[74:75] op_sel:[1,0]
	v_pk_fma_f32 v[76:77], v[144:145], v[76:77], v[140:141]
	v_pk_fma_f32 v[74:75], v[142:143], v[74:75], v[138:139]
	v_cndmask_b32_e32 v77, v77, v168, vcc
	v_cndmask_b32_e32 v76, v76, v168, vcc
	v_cndmask_b32_e32 v75, v75, v168, vcc
	v_cndmask_b32_e32 v74, v74, v168, vcc
	global_store_dwordx4 v[82:83], v[74:77], off offset:512
	v_pk_fma_f32 v[128:129], v[160:161], v[128:129], v[156:157]
	v_cndmask_b32_e32 v127, v127, v168, vcc
	v_sub_f32_e32 v75, v91, v180
	v_sub_f32_e32 v74, v90, v180
	v_sub_f32_e32 v77, v93, v180
	v_sub_f32_e32 v76, v92, v180
	v_pk_mul_f32 v[76:77], v[180:181], v[76:77] op_sel:[1,0]
	v_pk_mul_f32 v[74:75], v[180:181], v[74:75] op_sel:[1,0]
	v_pk_fma_f32 v[76:77], v[132:133], v[76:77], v[136:137]
	v_pk_fma_f32 v[74:75], v[130:131], v[74:75], v[134:135]
	v_cndmask_b32_e32 v77, v77, v168, vcc
	v_cndmask_b32_e32 v76, v76, v168, vcc
	v_cndmask_b32_e32 v75, v75, v168, vcc
	v_cndmask_b32_e32 v74, v74, v168, vcc
	v_cndmask_b32_e32 v129, v129, v168, vcc
	v_cndmask_b32_e32 v128, v128, v168, vcc
	v_cndmask_b32_e32 v126, v126, v168, vcc
	global_store_dwordx4 v[82:83], v[74:77], off offset:576
	global_store_dwordx4 v[82:83], v[126:129], off
	v_lshlrev_b64 v[82:83], 12, v[162:163]
	s_waitcnt lgkmcnt(0)
	v_sub_f32_e32 v75, v123, v78
	v_sub_f32_e32 v74, v122, v78
	v_sub_f32_e32 v77, v125, v78
	v_sub_f32_e32 v76, v124, v78
	v_pk_mul_f32 v[76:77], v[78:79], v[76:77] op_sel:[1,0]
	v_pk_mul_f32 v[74:75], v[78:79], v[74:75] op_sel:[1,0]
	v_pk_fma_f32 v[76:77], v[160:161], v[76:77], v[156:157]
	v_pk_fma_f32 v[74:75], v[158:159], v[74:75], v[154:155]
	v_lshl_add_u64 v[82:83], s[58:59], 0, v[82:83]
	v_cndmask_b32_e32 v77, v77, v168, vcc
	v_cndmask_b32_e32 v76, v76, v168, vcc
	v_cndmask_b32_e32 v75, v75, v168, vcc
	v_cndmask_b32_e32 v74, v74, v168, vcc
	v_lshl_add_u64 v[82:83], v[82:83], 0, v[0:1]
	global_store_dwordx4 v[82:83], v[74:77], off
	v_sub_f32_e32 v71, v71, v80
	v_sub_f32_e32 v70, v70, v80
	v_sub_f32_e32 v75, v119, v78
	v_sub_f32_e32 v74, v118, v78
	v_sub_f32_e32 v77, v121, v78
	v_sub_f32_e32 v76, v120, v78
	v_pk_mul_f32 v[76:77], v[78:79], v[76:77] op_sel:[1,0]
	v_pk_mul_f32 v[74:75], v[78:79], v[74:75] op_sel:[1,0]
	v_pk_fma_f32 v[76:77], v[148:149], v[76:77], v[152:153]
	v_pk_fma_f32 v[74:75], v[146:147], v[74:75], v[150:151]
	v_cndmask_b32_e32 v77, v77, v168, vcc
	v_cndmask_b32_e32 v76, v76, v168, vcc
	v_cndmask_b32_e32 v75, v75, v168, vcc
	v_cndmask_b32_e32 v74, v74, v168, vcc
	global_store_dwordx4 v[82:83], v[74:77], off offset:64
	v_sub_f32_e32 v73, v73, v80
	v_sub_f32_e32 v72, v72, v80
	v_sub_f32_e32 v75, v115, v78
	v_sub_f32_e32 v74, v114, v78
	v_sub_f32_e32 v77, v117, v78
	v_sub_f32_e32 v76, v116, v78
	v_pk_mul_f32 v[76:77], v[78:79], v[76:77] op_sel:[1,0]
	v_pk_mul_f32 v[74:75], v[78:79], v[74:75] op_sel:[1,0]
	v_pk_fma_f32 v[76:77], v[144:145], v[76:77], v[140:141]
	v_pk_fma_f32 v[74:75], v[142:143], v[74:75], v[138:139]
	v_cndmask_b32_e32 v77, v77, v168, vcc
	v_cndmask_b32_e32 v76, v76, v168, vcc
	v_cndmask_b32_e32 v75, v75, v168, vcc
	v_cndmask_b32_e32 v74, v74, v168, vcc
	global_store_dwordx4 v[82:83], v[74:77], off offset:512
	v_pk_mul_f32 v[72:73], v[80:81], v[72:73] op_sel:[1,0]
	v_pk_mul_f32 v[70:71], v[80:81], v[70:71] op_sel:[1,0]
	v_sub_f32_e32 v75, v107, v78
	v_sub_f32_e32 v74, v106, v78
	v_sub_f32_e32 v77, v109, v78
	v_sub_f32_e32 v76, v108, v78
	v_pk_mul_f32 v[76:77], v[78:79], v[76:77] op_sel:[1,0]
	v_pk_mul_f32 v[74:75], v[78:79], v[74:75] op_sel:[1,0]
	v_lshlrev_b64 v[78:79], 12, v[164:165]
	v_lshl_add_u64 v[78:79], s[58:59], 0, v[78:79]
	v_pk_fma_f32 v[70:71], v[142:143], v[70:71], v[138:139]
	v_pk_fma_f32 v[72:73], v[144:145], v[72:73], v[140:141]
	v_lshl_add_u64 v[78:79], v[78:79], 0, v[0:1]
	v_cndmask_b32_e32 v73, v73, v168, vcc
	v_cndmask_b32_e32 v72, v72, v168, vcc
	v_cndmask_b32_e32 v71, v71, v168, vcc
	v_cndmask_b32_e32 v70, v70, v168, vcc
	global_store_dwordx4 v[78:79], v[70:73], off offset:512
	ds_read2_b64 v[70:73], v169 offset0:128 offset1:144
	v_sub_f32_e32 v67, v67, v80
	v_sub_f32_e32 v66, v66, v80
	v_sub_f32_e32 v69, v69, v80
	v_sub_f32_e32 v68, v68, v80
	v_pk_mul_f32 v[68:69], v[80:81], v[68:69] op_sel:[1,0]
	v_pk_mul_f32 v[66:67], v[80:81], v[66:67] op_sel:[1,0]
	v_pk_fma_f32 v[68:69], v[132:133], v[68:69], v[136:137]
	v_pk_fma_f32 v[66:67], v[130:131], v[66:67], v[134:135]
	v_cndmask_b32_e32 v69, v69, v168, vcc
	v_cndmask_b32_e32 v68, v68, v168, vcc
	v_cndmask_b32_e32 v67, v67, v168, vcc
	v_cndmask_b32_e32 v66, v66, v168, vcc
	s_waitcnt lgkmcnt(0)
	v_sub_f32_e32 v51, v51, v70
	v_sub_f32_e32 v50, v50, v70
	v_sub_f32_e32 v53, v53, v70
	v_sub_f32_e32 v52, v52, v70
	global_store_dwordx4 v[78:79], v[66:69], off offset:576
	v_pk_mul_f32 v[52:53], v[70:71], v[52:53] op_sel:[1,0]
	v_pk_mul_f32 v[50:51], v[70:71], v[50:51] op_sel:[1,0]
	v_lshlrev_b64 v[66:67], 12, v[170:171]
	v_lshl_add_u64 v[66:67], s[58:59], 0, v[66:67]
	v_pk_fma_f32 v[50:51], v[130:131], v[50:51], v[134:135]
	v_pk_fma_f32 v[52:53], v[132:133], v[52:53], v[136:137]
	v_lshl_add_u64 v[66:67], v[66:67], 0, v[0:1]
	v_cndmask_b32_e32 v53, v53, v168, vcc
	v_cndmask_b32_e32 v52, v52, v168, vcc
	v_cndmask_b32_e32 v51, v51, v168, vcc
	v_cndmask_b32_e32 v50, v50, v168, vcc
	v_sub_f32_e32 v39, v39, v72
	v_sub_f32_e32 v38, v38, v72
	v_sub_f32_e32 v41, v41, v72
	v_sub_f32_e32 v40, v40, v72
	global_store_dwordx4 v[66:67], v[50:53], off offset:576
	v_pk_mul_f32 v[40:41], v[72:73], v[40:41] op_sel:[1,0]
	v_pk_mul_f32 v[38:39], v[72:73], v[38:39] op_sel:[1,0]
	v_lshlrev_b64 v[50:51], 12, v[172:173]
	v_lshl_add_u64 v[50:51], s[58:59], 0, v[50:51]
	v_pk_fma_f32 v[38:39], v[142:143], v[38:39], v[138:139]
	v_pk_fma_f32 v[40:41], v[144:145], v[40:41], v[140:141]
	v_lshl_add_u64 v[50:51], v[50:51], 0, v[0:1]
	v_cndmask_b32_e32 v41, v41, v168, vcc
	v_cndmask_b32_e32 v40, v40, v168, vcc
	v_cndmask_b32_e32 v39, v39, v168, vcc
	v_cndmask_b32_e32 v38, v38, v168, vcc
	global_store_dwordx4 v[50:51], v[38:41], off offset:512
	ds_read2_b64 v[38:41], v169 offset0:160 offset1:176
	v_sub_f32_e32 v35, v35, v72
	v_sub_f32_e32 v34, v34, v72
	v_sub_f32_e32 v37, v37, v72
	v_sub_f32_e32 v36, v36, v72
	v_pk_mul_f32 v[36:37], v[72:73], v[36:37] op_sel:[1,0]
	v_pk_mul_f32 v[34:35], v[72:73], v[34:35] op_sel:[1,0]
	v_pk_fma_f32 v[36:37], v[132:133], v[36:37], v[136:137]
	v_pk_fma_f32 v[34:35], v[130:131], v[34:35], v[134:135]
	v_cndmask_b32_e32 v37, v37, v168, vcc
	v_cndmask_b32_e32 v36, v36, v168, vcc
	v_cndmask_b32_e32 v35, v35, v168, vcc
	v_cndmask_b32_e32 v34, v34, v168, vcc
	s_waitcnt lgkmcnt(0)
	v_sub_f32_e32 v19, v19, v38
	v_sub_f32_e32 v18, v18, v38
	v_sub_f32_e32 v21, v21, v38
	v_sub_f32_e32 v20, v20, v38
	global_store_dwordx4 v[50:51], v[34:37], off offset:576
	v_pk_mul_f32 v[20:21], v[38:39], v[20:21] op_sel:[1,0]
	v_pk_mul_f32 v[18:19], v[38:39], v[18:19] op_sel:[1,0]
	v_lshlrev_b64 v[34:35], 12, v[174:175]
	v_pk_fma_f32 v[74:75], v[130:131], v[74:75], v[134:135]
	v_pk_fma_f32 v[76:77], v[132:133], v[76:77], v[136:137]
	v_lshl_add_u64 v[34:35], s[58:59], 0, v[34:35]
	v_pk_fma_f32 v[18:19], v[130:131], v[18:19], v[134:135]
	v_pk_fma_f32 v[20:21], v[132:133], v[20:21], v[136:137]
	v_cndmask_b32_e32 v77, v77, v168, vcc
	v_cndmask_b32_e32 v76, v76, v168, vcc
	v_cndmask_b32_e32 v75, v75, v168, vcc
	v_cndmask_b32_e32 v74, v74, v168, vcc
	v_lshl_add_u64 v[34:35], v[34:35], 0, v[0:1]
	v_cndmask_b32_e32 v21, v21, v168, vcc
	v_cndmask_b32_e32 v20, v20, v168, vcc
	v_cndmask_b32_e32 v19, v19, v168, vcc
	v_cndmask_b32_e32 v18, v18, v168, vcc
	global_store_dwordx4 v[82:83], v[74:77], off offset:576
	global_store_dwordx4 v[34:35], v[18:21], off offset:576
	v_sub_f32_e32 v63, v63, v70
	v_sub_f32_e32 v75, v99, v80
	v_lshlrev_b64 v[18:19], 12, v[176:177]
	v_lshl_add_u64 v[18:19], s[58:59], 0, v[18:19]
	v_lshl_add_u64 v[18:19], v[18:19], 0, v[0:1]
	v_sub_f32_e32 v1, v11, v40
	v_sub_f32_e32 v0, v10, v40
	v_sub_f32_e32 v11, v13, v40
	v_sub_f32_e32 v10, v12, v40
	v_pk_mul_f32 v[10:11], v[40:41], v[10:11] op_sel:[1,0]
	v_pk_mul_f32 v[0:1], v[40:41], v[0:1] op_sel:[1,0]
	v_sub_f32_e32 v74, v98, v80
	v_sub_f32_e32 v77, v101, v80
	v_sub_f32_e32 v76, v100, v80
	v_pk_fma_f32 v[0:1], v[146:147], v[0:1], v[150:151]
	v_pk_fma_f32 v[10:11], v[148:149], v[10:11], v[152:153]
	v_pk_mul_f32 v[76:77], v[80:81], v[76:77] op_sel:[1,0]
	v_pk_mul_f32 v[74:75], v[80:81], v[74:75] op_sel:[1,0]
	v_cndmask_b32_e32 v13, v11, v168, vcc
	v_cndmask_b32_e32 v12, v10, v168, vcc
	v_cndmask_b32_e32 v11, v1, v168, vcc
	v_cndmask_b32_e32 v10, v0, v168, vcc
	v_sub_f32_e32 v1, v7, v40
	v_sub_f32_e32 v0, v6, v40
	v_sub_f32_e32 v7, v9, v40
	v_sub_f32_e32 v6, v8, v40
	v_pk_fma_f32 v[74:75], v[158:159], v[74:75], v[154:155]
	v_pk_fma_f32 v[76:77], v[160:161], v[76:77], v[156:157]
	v_pk_mul_f32 v[6:7], v[40:41], v[6:7] op_sel:[1,0]
	v_pk_mul_f32 v[0:1], v[40:41], v[0:1] op_sel:[1,0]
	v_cndmask_b32_e32 v77, v77, v168, vcc
	v_cndmask_b32_e32 v76, v76, v168, vcc
	v_cndmask_b32_e32 v75, v75, v168, vcc
	v_cndmask_b32_e32 v74, v74, v168, vcc
	v_pk_fma_f32 v[0:1], v[142:143], v[0:1], v[138:139]
	v_pk_fma_f32 v[6:7], v[144:145], v[6:7], v[140:141]
	global_store_dwordx4 v[78:79], v[74:77], off
	v_sub_f32_e32 v62, v62, v70
	v_sub_f32_e32 v65, v65, v70
	v_sub_f32_e32 v75, v95, v80
	v_sub_f32_e32 v74, v94, v80
	v_sub_f32_e32 v77, v97, v80
	v_sub_f32_e32 v76, v96, v80
	v_sub_f32_e32 v64, v64, v70
	v_sub_f32_e32 v59, v59, v70
	v_sub_f32_e32 v58, v58, v70
	v_sub_f32_e32 v61, v61, v70
	v_sub_f32_e32 v60, v60, v70
	v_sub_f32_e32 v55, v55, v70
	v_sub_f32_e32 v54, v54, v70
	v_sub_f32_e32 v57, v57, v70
	v_sub_f32_e32 v56, v56, v70
	v_sub_f32_e32 v47, v47, v72
	v_sub_f32_e32 v46, v46, v72
	v_sub_f32_e32 v49, v49, v72
	v_sub_f32_e32 v48, v48, v72
	v_sub_f32_e32 v43, v43, v72
	v_sub_f32_e32 v42, v42, v72
	v_sub_f32_e32 v45, v45, v72
	v_sub_f32_e32 v44, v44, v72
	v_sub_f32_e32 v31, v31, v38
	v_sub_f32_e32 v30, v30, v38
	v_sub_f32_e32 v33, v33, v38
	v_sub_f32_e32 v32, v32, v38
	v_sub_f32_e32 v27, v27, v38
	v_sub_f32_e32 v26, v26, v38
	v_sub_f32_e32 v29, v29, v38
	v_sub_f32_e32 v28, v28, v38
	v_sub_f32_e32 v23, v23, v38
	v_sub_f32_e32 v22, v22, v38
	v_sub_f32_e32 v25, v25, v38
	v_sub_f32_e32 v24, v24, v38
	v_sub_f32_e32 v15, v15, v40
	v_sub_f32_e32 v14, v14, v40
	v_sub_f32_e32 v17, v17, v40
	v_sub_f32_e32 v16, v16, v40
	v_cndmask_b32_e32 v9, v7, v168, vcc
	v_cndmask_b32_e32 v8, v6, v168, vcc
	v_cndmask_b32_e32 v7, v1, v168, vcc
	v_cndmask_b32_e32 v6, v0, v168, vcc
	v_sub_f32_e32 v1, v3, v40
	v_sub_f32_e32 v0, v2, v40
	v_sub_f32_e32 v3, v5, v40
	v_sub_f32_e32 v2, v4, v40
	v_pk_mul_f32 v[76:77], v[80:81], v[76:77] op_sel:[1,0]
	v_pk_mul_f32 v[74:75], v[80:81], v[74:75] op_sel:[1,0]
	v_pk_mul_f32 v[64:65], v[70:71], v[64:65] op_sel:[1,0]
	v_pk_mul_f32 v[62:63], v[70:71], v[62:63] op_sel:[1,0]
	v_pk_mul_f32 v[60:61], v[70:71], v[60:61] op_sel:[1,0]
	v_pk_mul_f32 v[58:59], v[70:71], v[58:59] op_sel:[1,0]
	v_pk_mul_f32 v[56:57], v[70:71], v[56:57] op_sel:[1,0]
	v_pk_mul_f32 v[54:55], v[70:71], v[54:55] op_sel:[1,0]
	v_pk_mul_f32 v[48:49], v[72:73], v[48:49] op_sel:[1,0]
	v_pk_mul_f32 v[46:47], v[72:73], v[46:47] op_sel:[1,0]
	v_pk_mul_f32 v[44:45], v[72:73], v[44:45] op_sel:[1,0]
	v_pk_mul_f32 v[42:43], v[72:73], v[42:43] op_sel:[1,0]
	v_pk_mul_f32 v[32:33], v[38:39], v[32:33] op_sel:[1,0]
	v_pk_mul_f32 v[30:31], v[38:39], v[30:31] op_sel:[1,0]
	v_pk_mul_f32 v[28:29], v[38:39], v[28:29] op_sel:[1,0]
	v_pk_mul_f32 v[26:27], v[38:39], v[26:27] op_sel:[1,0]
	v_pk_mul_f32 v[24:25], v[38:39], v[24:25] op_sel:[1,0]
	v_pk_mul_f32 v[22:23], v[38:39], v[22:23] op_sel:[1,0]
	v_pk_mul_f32 v[16:17], v[40:41], v[16:17] op_sel:[1,0]
	v_pk_mul_f32 v[14:15], v[40:41], v[14:15] op_sel:[1,0]
	v_pk_mul_f32 v[2:3], v[40:41], v[2:3] op_sel:[1,0]
	v_pk_mul_f32 v[0:1], v[40:41], v[0:1] op_sel:[1,0]
	v_pk_fma_f32 v[74:75], v[146:147], v[74:75], v[150:151]
	v_pk_fma_f32 v[76:77], v[148:149], v[76:77], v[152:153]
	v_pk_fma_f32 v[62:63], v[158:159], v[62:63], v[154:155]
	v_pk_fma_f32 v[64:65], v[160:161], v[64:65], v[156:157]
	v_pk_fma_f32 v[58:59], v[146:147], v[58:59], v[150:151]
	v_pk_fma_f32 v[60:61], v[148:149], v[60:61], v[152:153]
	v_pk_fma_f32 v[54:55], v[142:143], v[54:55], v[138:139]
	v_pk_fma_f32 v[56:57], v[144:145], v[56:57], v[140:141]
	v_pk_fma_f32 v[46:47], v[158:159], v[46:47], v[154:155]
	v_pk_fma_f32 v[48:49], v[160:161], v[48:49], v[156:157]
	v_pk_fma_f32 v[42:43], v[146:147], v[42:43], v[150:151]
	v_pk_fma_f32 v[44:45], v[148:149], v[44:45], v[152:153]
	v_pk_fma_f32 v[30:31], v[158:159], v[30:31], v[154:155]
	v_pk_fma_f32 v[32:33], v[160:161], v[32:33], v[156:157]
	v_pk_fma_f32 v[26:27], v[146:147], v[26:27], v[150:151]
	v_pk_fma_f32 v[28:29], v[148:149], v[28:29], v[152:153]
	v_pk_fma_f32 v[22:23], v[142:143], v[22:23], v[138:139]
	v_pk_fma_f32 v[24:25], v[144:145], v[24:25], v[140:141]
	v_pk_fma_f32 v[14:15], v[158:159], v[14:15], v[154:155]
	v_pk_fma_f32 v[16:17], v[160:161], v[16:17], v[156:157]
	v_pk_fma_f32 v[0:1], v[130:131], v[0:1], v[134:135]
	v_pk_fma_f32 v[2:3], v[132:133], v[2:3], v[136:137]
	v_cndmask_b32_e32 v77, v77, v168, vcc
	v_cndmask_b32_e32 v76, v76, v168, vcc
	v_cndmask_b32_e32 v75, v75, v168, vcc
	v_cndmask_b32_e32 v74, v74, v168, vcc
	v_cndmask_b32_e32 v65, v65, v168, vcc
	v_cndmask_b32_e32 v64, v64, v168, vcc
	v_cndmask_b32_e32 v63, v63, v168, vcc
	v_cndmask_b32_e32 v62, v62, v168, vcc
	v_cndmask_b32_e32 v61, v61, v168, vcc
	v_cndmask_b32_e32 v60, v60, v168, vcc
	v_cndmask_b32_e32 v59, v59, v168, vcc
	v_cndmask_b32_e32 v58, v58, v168, vcc
	v_cndmask_b32_e32 v57, v57, v168, vcc
	v_cndmask_b32_e32 v56, v56, v168, vcc
	v_cndmask_b32_e32 v55, v55, v168, vcc
	v_cndmask_b32_e32 v54, v54, v168, vcc
	v_cndmask_b32_e32 v49, v49, v168, vcc
	v_cndmask_b32_e32 v48, v48, v168, vcc
	v_cndmask_b32_e32 v47, v47, v168, vcc
	v_cndmask_b32_e32 v46, v46, v168, vcc
	v_cndmask_b32_e32 v45, v45, v168, vcc
	v_cndmask_b32_e32 v44, v44, v168, vcc
	v_cndmask_b32_e32 v43, v43, v168, vcc
	v_cndmask_b32_e32 v42, v42, v168, vcc
	v_cndmask_b32_e32 v33, v33, v168, vcc
	v_cndmask_b32_e32 v32, v32, v168, vcc
	v_cndmask_b32_e32 v31, v31, v168, vcc
	v_cndmask_b32_e32 v30, v30, v168, vcc
	v_cndmask_b32_e32 v29, v29, v168, vcc
	v_cndmask_b32_e32 v28, v28, v168, vcc
	v_cndmask_b32_e32 v27, v27, v168, vcc
	v_cndmask_b32_e32 v26, v26, v168, vcc
	v_cndmask_b32_e32 v25, v25, v168, vcc
	v_cndmask_b32_e32 v24, v24, v168, vcc
	v_cndmask_b32_e32 v23, v23, v168, vcc
	v_cndmask_b32_e32 v22, v22, v168, vcc
	v_cndmask_b32_e32 v17, v17, v168, vcc
	v_cndmask_b32_e32 v16, v16, v168, vcc
	v_cndmask_b32_e32 v15, v15, v168, vcc
	v_cndmask_b32_e32 v14, v14, v168, vcc
	v_cndmask_b32_e32 v3, v3, v168, vcc
	v_cndmask_b32_e32 v2, v2, v168, vcc
	v_cndmask_b32_e32 v1, v1, v168, vcc
	v_cndmask_b32_e32 v0, v0, v168, vcc
	global_store_dwordx4 v[78:79], v[74:77], off offset:64
	global_store_dwordx4 v[66:67], v[62:65], off
	global_store_dwordx4 v[66:67], v[58:61], off offset:64
	global_store_dwordx4 v[66:67], v[54:57], off offset:512
	global_store_dwordx4 v[50:51], v[46:49], off
	global_store_dwordx4 v[50:51], v[42:45], off offset:64
	global_store_dwordx4 v[34:35], v[30:33], off
	global_store_dwordx4 v[34:35], v[26:29], off offset:64
	global_store_dwordx4 v[34:35], v[22:25], off offset:512
	global_store_dwordx4 v[18:19], v[14:17], off
	global_store_dwordx4 v[18:19], v[10:13], off offset:64
	global_store_dwordx4 v[18:19], v[6:9], off offset:512
	global_store_dwordx4 v[18:19], v[0:3], off offset:576
